# adds v_rsq for the per-row rstd in all rms-norm phases (P1,P7,P10,P14,P17) and the P3 statistics
# speedup vs baseline: 1.0028x; 1.0023x over previous
; __device__ __forceinline__ float wave_sum_fast(float x) { x = reduce16(x); return (rl_(x, 0) + rl_(x, 16)) + (rl_(x, 32) + rl_(x, 48)); }
; __device__ __forceinline__ void norm_mod_phase(const Ctx& F, const float* xin, const float* gain, const float* shift, const float* scale) {
;     ...
;         for (int r = 0; r < 32; r += 4) {
;             f32x4 v[4][4]; float s[4];
; #pragma unroll
;             for (int u = 0; u < 4; ++u) { const float* xr = xin + (size_t)(row0 + r + u) * D; s[u] = 0.f;
; #pragma unroll
;                 for (int j = 0; j < 4; ++j) v[u][j] = *(const f32x4*)(xr + 4 * ln + 256 * j); }
; #pragma unroll
;             for (int u = 0; u < 4; ++u) {
; #pragma unroll
;                 for (int j = 0; j < 4; ++j) s[u] += (v[u][j][0] * v[u][j][0] + v[u][j][1] * v[u][j][1]) + (v[u][j][2] * v[u][j][2] + v[u][j][3] * v[u][j][3]);
;                 s[u] = wave_sum_fast(s[u]); }
.LBB0_164:
	v_lshl_add_u64 v[28:29], s[36:37], 0, v[80:81]
	v_lshl_add_u64 v[30:31], s[40:41], 0, v[80:81]
	v_lshl_add_u64 v[106:107], s[54:55], 0, v[80:81]
	v_lshl_add_u64 v[110:111], s[30:31], 0, v[80:81]
	flat_load_dwordx4 v[76:79], v[28:29]
	flat_load_dwordx4 v[68:71], v[28:29] offset:1024
	flat_load_dwordx4 v[64:67], v[28:29] offset:3072
	flat_load_dwordx4 v[72:75], v[28:29] offset:2048
	flat_load_dwordx4 v[60:63], v[30:31]
	flat_load_dwordx4 v[56:59], v[30:31] offset:1024
	flat_load_dwordx4 v[52:55], v[30:31] offset:2048
	flat_load_dwordx4 v[48:51], v[30:31] offset:3072
	flat_load_dwordx4 v[44:47], v[106:107]
	flat_load_dwordx4 v[40:43], v[106:107] offset:1024
	flat_load_dwordx4 v[36:39], v[106:107] offset:2048
	flat_load_dwordx4 v[32:35], v[106:107] offset:3072
	flat_load_dwordx4 v[24:27], v[110:111]
	flat_load_dwordx4 v[20:23], v[110:111] offset:1024
	flat_load_dwordx4 v[16:19], v[110:111] offset:2048
	flat_load_dwordx4 v[28:31], v[110:111] offset:3072
	v_lshl_add_u64 v[108:109], s[28:29], 0, v[88:89]
	v_add_co_u32_e32 v112, vcc, s42, v108
	v_lshl_add_u64 v[118:119], s[38:39], 0, v[88:89]
	s_nop 0
	v_addc_co_u32_e32 v113, vcc, 0, v109, vcc
	v_add_co_u32_e32 v110, vcc, s42, v118
	v_lshl_add_u64 v[120:121], s[52:53], 0, v[88:89]
	s_nop 0
	v_addc_co_u32_e32 v111, vcc, 0, v119, vcc
	v_add_co_u32_e32 v108, vcc, s42, v120
	v_lshl_add_u64 v[122:123], s[34:35], 0, v[88:89]
	s_nop 0
	v_addc_co_u32_e32 v109, vcc, 0, v121, vcc
	v_add_co_u32_e32 v106, vcc, s42, v122
	s_add_u32 s28, s28, 0x2000
	s_nop 0
	v_addc_co_u32_e32 v107, vcc, 0, v123, vcc
	s_addc_u32 s29, s29, 0
	s_add_i32 s21, s21, 4
	s_add_u32 s30, s30, 0x4000
	s_addc_u32 s31, s31, 0
	s_add_u32 s34, s34, 0x2000
	s_addc_u32 s35, s35, 0
	s_add_u32 s36, s36, 0x4000
	s_addc_u32 s37, s37, 0
	s_add_u32 s38, s38, 0x2000
	s_addc_u32 s39, s39, 0
	s_add_u32 s40, s40, 0x4000
	s_addc_u32 s41, s41, 0
	s_add_u32 s52, s52, 0x2000
	s_addc_u32 s53, s53, 0
	s_add_u32 s54, s54, 0x4000
	s_addc_u32 s55, s55, 0
	s_cmp_gt_u32 s21, 27
	s_waitcnt vmcnt(0) lgkmcnt(0)
	v_pk_mul_f32 v[118:119], v[78:79], v[78:79]
	v_pk_mul_f32 v[120:121], v[76:77], v[76:77]
	v_pk_mul_f32 v[122:123], v[70:71], v[70:71]
	v_pk_mul_f32 v[124:125], v[68:69], v[68:69]
	v_mul_f32_e32 v126, v73, v73
	v_mul_f32_e32 v128, v75, v75
	v_pk_mul_f32 v[130:131], v[62:63], v[62:63]
	v_pk_mul_f32 v[132:133], v[60:61], v[60:61]
	v_pk_mul_f32 v[134:135], v[58:59], v[58:59]
	v_pk_mul_f32 v[136:137], v[56:57], v[56:57]
	v_mul_f32_e32 v138, v53, v53
	v_mul_f32_e32 v140, v55, v55
	v_pk_mul_f32 v[142:143], v[46:47], v[46:47]
	v_pk_mul_f32 v[144:145], v[44:45], v[44:45]
	v_pk_mul_f32 v[146:147], v[42:43], v[42:43]
	v_pk_mul_f32 v[148:149], v[40:41], v[40:41]
	v_pk_mov_b32 v[166:167], v[120:121], v[118:119] op_sel:[1,0]
	v_mov_b32_e32 v121, v119
	v_pk_mov_b32 v[118:119], v[124:125], v[122:123] op_sel:[1,0]
	v_mov_b32_e32 v125, v123
	v_mul_f32_e32 v150, v37, v37
	v_mul_f32_e32 v152, v39, v39
	v_pk_mul_f32 v[154:155], v[26:27], v[26:27]
	v_pk_mul_f32 v[156:157], v[24:25], v[24:25]
	v_pk_mul_f32 v[158:159], v[22:23], v[22:23]
	v_pk_mul_f32 v[160:161], v[20:21], v[20:21]
	v_pk_fma_f32 v[122:123], v[72:73], v[72:73], v[126:127] op_sel_hi:[1,1,0]
	v_pk_fma_f32 v[126:127], v[74:75], v[74:75], v[128:129] op_sel_hi:[1,1,0]
	v_pk_mov_b32 v[128:129], v[132:133], v[130:131] op_sel:[1,0]
	v_mov_b32_e32 v133, v131
	v_pk_mov_b32 v[130:131], v[136:137], v[134:135] op_sel:[1,0]
	v_mov_b32_e32 v137, v135
	v_pk_fma_f32 v[134:135], v[52:53], v[52:53], v[138:139] op_sel_hi:[1,1,0]
	v_pk_fma_f32 v[138:139], v[54:55], v[54:55], v[140:141] op_sel_hi:[1,1,0]
	v_pk_mov_b32 v[140:141], v[144:145], v[142:143] op_sel:[1,0]
	v_mov_b32_e32 v145, v143
	v_pk_mov_b32 v[142:143], v[148:149], v[146:147] op_sel:[1,0]
	v_mov_b32_e32 v149, v147
	v_pk_add_f32 v[120:121], v[166:167], v[120:121]
	v_pk_add_f32 v[118:119], v[118:119], v[124:125]
	v_mul_f32_e32 v117, v66, v66
	v_mul_f32_e32 v165, v67, v67
	v_mul_f32_e32 v168, v64, v64
	v_mul_f32_e32 v169, v65, v65
	v_pk_fma_f32 v[146:147], v[36:37], v[36:37], v[150:151] op_sel_hi:[1,1,0]
	v_pk_fma_f32 v[150:151], v[38:39], v[38:39], v[152:153] op_sel_hi:[1,1,0]
	v_pk_mov_b32 v[152:153], v[156:157], v[154:155] op_sel:[1,0]
	v_mov_b32_e32 v157, v155
	v_pk_mov_b32 v[154:155], v[160:161], v[158:159] op_sel:[1,0]
	v_mov_b32_e32 v161, v159
	v_pk_add_f32 v[124:125], v[128:129], v[132:133]
	v_pk_add_f32 v[128:129], v[130:131], v[136:137]
	v_pk_add_f32 v[130:131], v[140:141], v[144:145]
	v_pk_add_f32 v[132:133], v[142:143], v[148:149]
	v_pk_add_f32 v[120:121], v[120:121], v[120:121] op_sel:[0,1] op_sel_hi:[1,0]
	v_pk_add_f32 v[118:119], v[118:119], v[118:119] op_sel:[0,1] op_sel_hi:[1,0]
	v_mul_f32_e32 v170, v50, v50
	v_mul_f32_e32 v171, v51, v51
	v_mul_f32_e32 v172, v48, v48
	v_mul_f32_e32 v173, v49, v49
	v_mul_f32_e32 v174, v34, v34
	v_mul_f32_e32 v175, v35, v35
	v_mul_f32_e32 v176, v32, v32
	v_mul_f32_e32 v177, v33, v33
	v_mul_f32_e32 v162, v17, v17
	v_mul_f32_e32 v164, v19, v19
	v_mov_b32_e32 v123, v117
	v_mov_b32_e32 v127, v165
	v_pk_add_f32 v[136:137], v[152:153], v[156:157]
	v_pk_add_f32 v[140:141], v[154:155], v[160:161]
	v_pk_add_f32 v[124:125], v[124:125], v[124:125] op_sel:[0,1] op_sel_hi:[1,0]
	v_pk_add_f32 v[128:129], v[128:129], v[128:129] op_sel:[0,1] op_sel_hi:[1,0]
	v_pk_add_f32 v[130:131], v[130:131], v[130:131] op_sel:[0,1] op_sel_hi:[1,0]
	v_pk_add_f32 v[132:133], v[132:133], v[132:133] op_sel:[0,1] op_sel_hi:[1,0]
	v_mov_b32_e32 v121, v168
	v_mov_b32_e32 v119, v169
	v_mul_f32_e32 v178, v30, v30
	v_mul_f32_e32 v179, v31, v31
	v_mul_f32_e32 v180, v28, v28
	v_mul_f32_e32 v181, v29, v29
	v_pk_fma_f32 v[158:159], v[16:17], v[16:17], v[162:163] op_sel_hi:[1,1,0]
; __device__ __forceinline__ unsigned pk2(float lo, float hi) { f32x2 v = {lo, hi}; bf16x2_t b = __builtin_convertvector(v, bf16x2_t); return __builtin_bit_cast(unsigned, b); }
; __device__ __forceinline__ float wave_sum_fast(float x) { x = reduce16(x); return (rl_(x, 0) + rl_(x, 16)) + (rl_(x, 32) + rl_(x, 48)); }
; __device__ __forceinline__ void norm_mod_phase(const Ctx& F, const float* xin, const float* gain, const float* shift, const float* scale) {
;     ...
;             for (int u = 0; u < 4; ++u) {
; #pragma unroll
;                 for (int j = 0; j < 4; ++j) s[u] += (v[u][j][0] * v[u][j][0] + v[u][j][1] * v[u][j][1]) + (v[u][j][2] * v[u][j][2] + v[u][j][3] * v[u][j][3]);
;                 s[u] = wave_sum_fast(s[u]); }
; #pragma unroll
;             for (int u = 0; u < 4; ++u) { const float rstd = 1.0f / sqrtf(s[u] * (1.0f / D) + 1e-6f);
; #pragma unroll
;                 for (int j = 0; j < 4; ++j) { const f32x4 o = v[u][j] * rstd * ga[j] + sh[j]; u32x2 w; w.x = pk2(o[0], o[1]); w.y = pk2(o[2], o[3]);
	v_pk_fma_f32 v[162:163], v[18:19], v[18:19], v[164:165] op_sel_hi:[1,1,0]
	v_mov_b32_e32 v135, v170
	v_mov_b32_e32 v139, v171
	v_mov_b32_e32 v147, v174
	v_mov_b32_e32 v151, v175
	v_pk_add_f32 v[122:123], v[122:123], v[126:127]
	v_pk_add_f32 v[136:137], v[136:137], v[136:137] op_sel:[0,1] op_sel_hi:[1,0]
	v_pk_add_f32 v[140:141], v[140:141], v[140:141] op_sel:[0,1] op_sel_hi:[1,0]
	v_mov_b32_e32 v125, v172
	v_mov_b32_e32 v129, v173
	v_mov_b32_e32 v131, v176
	v_mov_b32_e32 v133, v177
	v_pk_add_f32 v[118:119], v[120:121], v[118:119]
	v_mov_b32_e32 v159, v178
	v_mov_b32_e32 v163, v179
	v_pk_add_f32 v[126:127], v[134:135], v[138:139]
	v_pk_add_f32 v[134:135], v[146:147], v[150:151]
	v_mov_b32_e32 v137, v180
	v_mov_b32_e32 v141, v181
	v_pk_add_f32 v[120:121], v[124:125], v[128:129]
	v_pk_add_f32 v[124:125], v[130:131], v[132:133]
	v_pk_add_f32 v[118:119], v[118:119], v[122:123]
	v_pk_add_f32 v[138:139], v[158:159], v[162:163]
	v_pk_add_f32 v[128:129], v[136:137], v[140:141]
	v_pk_add_f32 v[120:121], v[120:121], v[126:127]
	v_pk_add_f32 v[122:123], v[124:125], v[134:135]
	v_add_f32_e32 v117, v118, v119
	v_pk_add_f32 v[124:125], v[128:129], v[138:139]
	v_add_f32_e32 v118, v120, v121
	v_add_f32_e32 v119, v122, v123
	v_add_f32_dpp v117, v117, v117 quad_perm:[1,0,3,2] row_mask:0xf bank_mask:0xf bound_ctrl:1
	v_add_f32_e32 v120, v124, v125
	v_add_f32_dpp v118, v118, v118 quad_perm:[1,0,3,2] row_mask:0xf bank_mask:0xf bound_ctrl:1
	v_add_f32_dpp v119, v119, v119 quad_perm:[1,0,3,2] row_mask:0xf bank_mask:0xf bound_ctrl:1
	v_add_f32_dpp v117, v117, v117 quad_perm:[2,3,0,1] row_mask:0xf bank_mask:0xf bound_ctrl:1
	v_add_f32_dpp v120, v120, v120 quad_perm:[1,0,3,2] row_mask:0xf bank_mask:0xf bound_ctrl:1
	v_add_f32_dpp v118, v118, v118 quad_perm:[2,3,0,1] row_mask:0xf bank_mask:0xf bound_ctrl:1
	v_add_f32_dpp v119, v119, v119 quad_perm:[2,3,0,1] row_mask:0xf bank_mask:0xf bound_ctrl:1
	v_add_f32_dpp v117, v117, v117 row_half_mirror row_mask:0xf bank_mask:0xf bound_ctrl:1
	v_add_f32_dpp v120, v120, v120 quad_perm:[2,3,0,1] row_mask:0xf bank_mask:0xf bound_ctrl:1
	v_add_f32_dpp v118, v118, v118 row_half_mirror row_mask:0xf bank_mask:0xf bound_ctrl:1
	v_add_f32_dpp v119, v119, v119 row_half_mirror row_mask:0xf bank_mask:0xf bound_ctrl:1
	v_add_f32_dpp v117, v117, v117 row_mirror row_mask:0xf bank_mask:0xf bound_ctrl:1
	v_add_f32_dpp v120, v120, v120 row_half_mirror row_mask:0xf bank_mask:0xf bound_ctrl:1
	v_add_f32_dpp v118, v118, v118 row_mirror row_mask:0xf bank_mask:0xf bound_ctrl:1
	v_add_f32_dpp v119, v119, v119 row_mirror row_mask:0xf bank_mask:0xf bound_ctrl:1
	v_readlane_b32 s12, v117, 16
	v_readlane_b32 s13, v117, 48
	v_add_f32_dpp v120, v120, v120 row_mirror row_mask:0xf bank_mask:0xf bound_ctrl:1
	v_readlane_b32 s4, v117, 0
	v_readlane_b32 s5, v117, 32
	v_readlane_b32 s6, v118, 0
	v_readlane_b32 s14, v118, 16
	v_readlane_b32 s7, v118, 32
	v_readlane_b32 s15, v118, 48
	v_readlane_b32 s8, v119, 0
	v_readlane_b32 s16, v119, 16
	v_readlane_b32 s9, v119, 32
	v_readlane_b32 s17, v119, 48
	v_mov_b32_e32 v118, s12
	v_mov_b32_e32 v119, s13
	v_readlane_b32 s10, v120, 0
	v_readlane_b32 s23, v120, 16
	v_readlane_b32 s11, v120, 32
	v_readlane_b32 s25, v120, 48
	v_mov_b32_e32 v120, s14
	v_mov_b32_e32 v121, s15
	v_mov_b32_e32 v122, s16
	v_mov_b32_e32 v123, s17
	v_pk_add_f32 v[118:119], s[4:5], v[118:119]
	v_pk_add_f32 v[120:121], s[6:7], v[120:121]
	v_pk_add_f32 v[122:123], s[8:9], v[122:123]
	v_add_f32_e32 v117, v118, v119
	v_mov_b32_e32 v124, s23
	v_mov_b32_e32 v125, s25
	v_add_f32_e32 v118, v120, v121
	v_add_f32_e32 v119, v122, v123
	v_fmamk_f32 v117, v117, 0x3a800000, v115
	v_pk_add_f32 v[124:125], s[10:11], v[124:125]
	v_fmamk_f32 v118, v118, 0x3a800000, v115
	v_fmamk_f32 v119, v119, 0x3a800000, v115
	v_rsq_f32_e32 v200, v117
	v_add_f32_e32 v120, v124, v125
	v_rsq_f32_e32 v201, v118
	v_rsq_f32_e32 v202, v119
	v_fmamk_f32 v120, v120, 0x3a800000, v115
	v_rsq_f32_e32 v203, v120
	v_mov_b32_e32 v118, v200
	v_pk_mul_f32 v[76:77], v[76:77], v[118:119] op_sel_hi:[1,0]
	v_pk_mul_f32 v[78:79], v[78:79], v[118:119] op_sel_hi:[1,0]
	v_pk_mul_f32 v[68:69], v[68:69], v[118:119] op_sel_hi:[1,0]
	v_pk_mul_f32 v[70:71], v[70:71], v[118:119] op_sel_hi:[1,0]
	v_pk_mul_f32 v[72:73], v[72:73], v[118:119] op_sel_hi:[1,0]
	v_pk_mul_f32 v[74:75], v[74:75], v[118:119] op_sel_hi:[1,0]
	v_pk_mul_f32 v[64:65], v[64:65], v[118:119] op_sel_hi:[1,0]
	v_pk_mul_f32 v[66:67], v[66:67], v[118:119] op_sel_hi:[1,0]
	v_mov_b32_e32 v118, v201
	v_pk_mul_f32 v[60:61], v[60:61], v[118:119] op_sel_hi:[1,0]
	v_pk_mul_f32 v[62:63], v[62:63], v[118:119] op_sel_hi:[1,0]
	v_pk_mul_f32 v[56:57], v[56:57], v[118:119] op_sel_hi:[1,0]
	v_pk_mul_f32 v[58:59], v[58:59], v[118:119] op_sel_hi:[1,0]
	v_pk_mul_f32 v[52:53], v[52:53], v[118:119] op_sel_hi:[1,0]
	v_pk_mul_f32 v[54:55], v[54:55], v[118:119] op_sel_hi:[1,0]
	v_pk_mul_f32 v[48:49], v[48:49], v[118:119] op_sel_hi:[1,0]
; __device__ __forceinline__ unsigned pk2(float lo, float hi) { f32x2 v = {lo, hi}; bf16x2_t b = __builtin_convertvector(v, bf16x2_t); return __builtin_bit_cast(unsigned, b); }
; __device__ __forceinline__ void norm_mod_phase(const Ctx& F, const float* xin, const float* gain, const float* shift, const float* scale) {
;     ...
;             for (int u = 0; u < 4; ++u) { const float rstd = 1.0f / sqrtf(s[u] * (1.0f / D) + 1e-6f);
; #pragma unroll
;                 for (int j = 0; j < 4; ++j) { const f32x4 o = v[u][j] * rstd * ga[j] + sh[j]; u32x2 w; w.x = pk2(o[0], o[1]); w.y = pk2(o[2], o[3]);
;                     *(u32x2*)(hb + (size_t)(row0 + r + u) * D + 4 * ln + 256 * j) = w; } }
	v_pk_mul_f32 v[50:51], v[50:51], v[118:119] op_sel_hi:[1,0]
	v_mov_b32_e32 v118, v202
	v_pk_fma_f32 v[66:67], v[102:103], v[66:67], v[14:15]
	v_pk_fma_f32 v[64:65], v[104:105], v[64:65], v[12:13]
	v_cvt_pk_bf16_f32 v64, v64, v65
	v_cvt_pk_bf16_f32 v65, v66, v67
	v_mov_b32_e32 v66, v203
	v_pk_mul_f32 v[44:45], v[44:45], v[118:119] op_sel_hi:[1,0]
	v_pk_mul_f32 v[46:47], v[46:47], v[118:119] op_sel_hi:[1,0]
	v_pk_mul_f32 v[24:25], v[24:25], v[66:67] op_sel_hi:[1,0]
	v_pk_mul_f32 v[26:27], v[26:27], v[66:67] op_sel_hi:[1,0]
	v_pk_fma_f32 v[78:79], v[90:91], v[78:79], v[2:3]
	v_pk_fma_f32 v[76:77], v[92:93], v[76:77], v[0:1]
	v_pk_mul_f32 v[40:41], v[40:41], v[118:119] op_sel_hi:[1,0]
	v_pk_mul_f32 v[42:43], v[42:43], v[118:119] op_sel_hi:[1,0]
	v_pk_mul_f32 v[36:37], v[36:37], v[118:119] op_sel_hi:[1,0]
	v_pk_mul_f32 v[38:39], v[38:39], v[118:119] op_sel_hi:[1,0]
	v_pk_mul_f32 v[32:33], v[32:33], v[118:119] op_sel_hi:[1,0]
	v_pk_mul_f32 v[34:35], v[34:35], v[118:119] op_sel_hi:[1,0]
	v_pk_fma_f32 v[62:63], v[90:91], v[62:63], v[2:3]
	v_pk_fma_f32 v[60:61], v[92:93], v[60:61], v[0:1]
	v_pk_mul_f32 v[20:21], v[20:21], v[66:67] op_sel_hi:[1,0]
	v_pk_mul_f32 v[22:23], v[22:23], v[66:67] op_sel_hi:[1,0]
	v_pk_mul_f32 v[16:17], v[16:17], v[66:67] op_sel_hi:[1,0]
	v_pk_mul_f32 v[18:19], v[18:19], v[66:67] op_sel_hi:[1,0]
	v_pk_mul_f32 v[28:29], v[28:29], v[66:67] op_sel_hi:[1,0]
	v_pk_mul_f32 v[30:31], v[30:31], v[66:67] op_sel_hi:[1,0]
	v_pk_fma_f32 v[46:47], v[90:91], v[46:47], v[2:3]
	v_pk_fma_f32 v[44:45], v[92:93], v[44:45], v[0:1]
	v_pk_fma_f32 v[26:27], v[90:91], v[26:27], v[2:3]
	v_pk_fma_f32 v[24:25], v[92:93], v[24:25], v[0:1]
	v_pk_fma_f32 v[70:71], v[94:95], v[70:71], v[6:7]
	v_pk_fma_f32 v[68:69], v[96:97], v[68:69], v[4:5]
	v_pk_fma_f32 v[74:75], v[98:99], v[74:75], v[10:11]
	v_pk_fma_f32 v[72:73], v[100:101], v[72:73], v[8:9]
	v_cvt_pk_bf16_f32 v76, v76, v77
	v_cvt_pk_bf16_f32 v77, v78, v79
	v_pk_fma_f32 v[58:59], v[94:95], v[58:59], v[6:7]
	v_pk_fma_f32 v[56:57], v[96:97], v[56:57], v[4:5]
	v_pk_fma_f32 v[54:55], v[98:99], v[54:55], v[10:11]
	v_pk_fma_f32 v[52:53], v[100:101], v[52:53], v[8:9]
	v_pk_fma_f32 v[50:51], v[102:103], v[50:51], v[14:15]
	v_pk_fma_f32 v[48:49], v[104:105], v[48:49], v[12:13]
	v_cvt_pk_bf16_f32 v60, v60, v61
	v_cvt_pk_bf16_f32 v61, v62, v63
	v_pk_fma_f32 v[42:43], v[94:95], v[42:43], v[6:7]
	v_pk_fma_f32 v[40:41], v[96:97], v[40:41], v[4:5]
	v_pk_fma_f32 v[38:39], v[98:99], v[38:39], v[10:11]
	v_pk_fma_f32 v[36:37], v[100:101], v[36:37], v[8:9]
	v_pk_fma_f32 v[34:35], v[102:103], v[34:35], v[14:15]
	v_pk_fma_f32 v[32:33], v[104:105], v[32:33], v[12:13]
	v_cvt_pk_bf16_f32 v44, v44, v45
	v_cvt_pk_bf16_f32 v45, v46, v47
	v_pk_fma_f32 v[22:23], v[94:95], v[22:23], v[6:7]
	v_pk_fma_f32 v[20:21], v[96:97], v[20:21], v[4:5]
	v_pk_fma_f32 v[18:19], v[98:99], v[18:19], v[10:11]
	v_pk_fma_f32 v[16:17], v[100:101], v[16:17], v[8:9]
	v_pk_fma_f32 v[30:31], v[102:103], v[30:31], v[14:15]
	v_pk_fma_f32 v[28:29], v[104:105], v[28:29], v[12:13]
	v_cvt_pk_bf16_f32 v24, v24, v25
	v_cvt_pk_bf16_f32 v25, v26, v27
	v_cvt_pk_bf16_f32 v68, v68, v69
	v_cvt_pk_bf16_f32 v69, v70, v71
	v_cvt_pk_bf16_f32 v70, v72, v73
	v_cvt_pk_bf16_f32 v71, v74, v75
	global_store_dwordx2 v[112:113], v[76:77], off
	global_store_dwordx2 v[112:113], v[68:69], off offset:512
	global_store_dwordx2 v[112:113], v[70:71], off offset:1024
	global_store_dwordx2 v[112:113], v[64:65], off offset:1536
	v_cvt_pk_bf16_f32 v56, v56, v57
	v_cvt_pk_bf16_f32 v57, v58, v59
	v_cvt_pk_bf16_f32 v52, v52, v53
	v_cvt_pk_bf16_f32 v53, v54, v55
	v_cvt_pk_bf16_f32 v48, v48, v49
	v_cvt_pk_bf16_f32 v49, v50, v51
	global_store_dwordx2 v[110:111], v[60:61], off
	global_store_dwordx2 v[110:111], v[56:57], off offset:512
	global_store_dwordx2 v[110:111], v[52:53], off offset:1024
	global_store_dwordx2 v[110:111], v[48:49], off offset:1536
	v_cvt_pk_bf16_f32 v40, v40, v41
	v_cvt_pk_bf16_f32 v41, v42, v43
	v_cvt_pk_bf16_f32 v36, v36, v37
	v_cvt_pk_bf16_f32 v37, v38, v39
	v_cvt_pk_bf16_f32 v32, v32, v33
	v_cvt_pk_bf16_f32 v33, v34, v35
	global_store_dwordx2 v[108:109], v[44:45], off
	global_store_dwordx2 v[108:109], v[40:41], off offset:512
	global_store_dwordx2 v[108:109], v[36:37], off offset:1024
	global_store_dwordx2 v[108:109], v[32:33], off offset:1536
	v_cvt_pk_bf16_f32 v20, v20, v21
	v_cvt_pk_bf16_f32 v21, v22, v23
	v_cvt_pk_bf16_f32 v16, v16, v17
	v_cvt_pk_bf16_f32 v17, v18, v19
	v_cvt_pk_bf16_f32 v18, v28, v29
	v_cvt_pk_bf16_f32 v19, v30, v31
	global_store_dwordx2 v[106:107], v[24:25], off
	global_store_dwordx2 v[106:107], v[20:21], off offset:512
	global_store_dwordx2 v[106:107], v[16:17], off offset:1024
	global_store_dwordx2 v[106:107], v[18:19], off offset:1536
	s_cbranch_scc0 .LBB0_164
	s_add_i32 s0, s0, s1
	s_add_i32 s20, s20, s3
	s_add_i32 s22, s22, s3
	s_add_i32 s24, s24, s3
	s_add_i32 s26, s26, s3
	s_cmpk_gt_i32 s0, 0x7ff
	s_cbranch_scc0 .LBB0_163

; __device__ __forceinline__ float wave_sum_fast(float x) { x = reduce16(x); return (rl_(x, 0) + rl_(x, 16)) + (rl_(x, 32) + rl_(x, 48)); }
; __device__ __forceinline__ void norm_mod_bf16_phase(const Ctx& F, const bf16_t* xin, const float* gain, const float* shift, const float* scale) {
;     ...
;         for (int r = 0; r < 32; r += 4) {
;             u32x4 raw[4][2]; float s[4];
; #pragma unroll
;             for (int u = 0; u < 4; ++u)
; #pragma unroll
;                 for (int j = 0; j < 2; ++j) raw[u][j] = *(const u32x4*)(xin + (size_t)(row0 + r + u) * D + 8 * ln + 512 * j);
; #pragma unroll
;             for (int u = 0; u < 4; ++u) { s[u] = 0.f;
; #pragma unroll
;                 for (int j = 0; j < 2; ++j) { float f[8]; unpack8(raw[u][j], f);
; #pragma unroll
;                     for (int e = 0; e < 8; ++e) s[u] += f[e] * f[e]; }
;                 s[u] = wave_sum_fast(s[u]); }
.LBB0_984:
	v_lshl_add_u64 v[40:41], s[28:29], 0, v[22:23]
	v_lshl_add_u64 v[42:43], s[36:37], 0, v[22:23]
	v_lshl_add_u64 v[44:45], s[56:57], 0, v[22:23]
	v_lshl_add_u64 v[46:47], s[34:35], 0, v[22:23]
	global_load_dwordx4 v[60:63], v[40:41], off
	global_load_dwordx4 v[68:71], v[42:43], off
	global_load_dwordx4 v[72:75], v[44:45], off
	global_load_dwordx4 v[116:119], v[46:47], off offset:1024
	global_load_dwordx4 v[84:87], v[40:41], off offset:-1024
	global_load_dwordx4 v[88:91], v[42:43], off offset:-1024
	global_load_dwordx4 v[120:123], v[44:45], off offset:-1024
	global_load_dwordx4 v[124:127], v[46:47], off
	v_lshl_add_u64 v[48:49], s[26:27], 0, v[22:23]
	v_add_co_u32_e32 v46, vcc, s48, v48
	v_lshl_add_u64 v[50:51], s[30:31], 0, v[22:23]
	s_nop 0
	v_addc_co_u32_e32 v47, vcc, 0, v49, vcc
	v_add_co_u32_e32 v44, vcc, s48, v50
	v_lshl_add_u64 v[52:53], s[38:39], 0, v[22:23]
	s_nop 0
	v_addc_co_u32_e32 v45, vcc, 0, v51, vcc
	v_add_co_u32_e32 v42, vcc, s48, v52
	v_lshl_add_u64 v[54:55], s[40:41], 0, v[22:23]
	s_nop 0
	v_addc_co_u32_e32 v43, vcc, 0, v53, vcc
	v_add_co_u32_e32 v40, vcc, s48, v54
	s_add_u32 s26, s26, 0x2000
	s_nop 0
	v_addc_co_u32_e32 v41, vcc, 0, v55, vcc
	s_addc_u32 s27, s27, 0
	s_add_i32 s19, s19, 4
	s_add_u32 s28, s28, 0x2000
	s_addc_u32 s29, s29, 0
	s_add_u32 s30, s30, 0x2000
	s_addc_u32 s31, s31, 0
	s_add_u32 s34, s34, 0x2000
	s_addc_u32 s35, s35, 0
	s_add_u32 s36, s36, 0x2000
	s_addc_u32 s37, s37, 0
	s_add_u32 s38, s38, 0x2000
	s_addc_u32 s39, s39, 0
	s_add_u32 s40, s40, 0x2000
	s_addc_u32 s41, s41, 0
	s_add_u32 s56, s56, 0x2000
	s_addc_u32 s57, s57, 0
	s_cmp_gt_u32 s19, 27
	s_waitcnt vmcnt(7)
	v_and_b32_e32 v80, 0xffff0000, v62
	s_waitcnt vmcnt(6)
	v_and_b32_e32 v64, 0xffff0000, v69
	s_waitcnt vmcnt(5)
	v_and_b32_e32 v56, 0xffff0000, v74
	v_lshlrev_b32_e32 v57, 16, v74
	s_waitcnt vmcnt(3)
	v_lshlrev_b32_e32 v110, 16, v84
	v_and_b32_e32 v111, 0xffff0000, v84
	v_lshlrev_b32_e32 v106, 16, v85
	v_and_b32_e32 v107, 0xffff0000, v85
	s_waitcnt vmcnt(2)
	v_lshlrev_b32_e32 v92, 16, v91
	v_and_b32_e32 v93, 0xffff0000, v91
	v_lshlrev_b32_e32 v94, 16, v90
	v_and_b32_e32 v95, 0xffff0000, v90
	v_lshlrev_b32_e32 v100, 16, v88
	v_and_b32_e32 v101, 0xffff0000, v88
	s_waitcnt vmcnt(1)
	v_lshlrev_b32_e32 v90, 16, v120
	v_and_b32_e32 v91, 0xffff0000, v120
	v_pk_mul_f32 v[146:147], v[110:111], v[110:111]
	v_and_b32_e32 v58, 0xffff0000, v75
	v_lshlrev_b32_e32 v59, 16, v75
	v_lshlrev_b32_e32 v102, 16, v87
	v_and_b32_e32 v103, 0xffff0000, v87
	v_lshlrev_b32_e32 v104, 16, v86
	v_and_b32_e32 v105, 0xffff0000, v86
	v_lshlrev_b32_e32 v96, 16, v89
	v_and_b32_e32 v97, 0xffff0000, v89
	v_lshlrev_b32_e32 v86, 16, v121
	v_and_b32_e32 v87, 0xffff0000, v121
	s_waitcnt vmcnt(0)
	v_lshlrev_b32_e32 v74, 16, v124
	v_and_b32_e32 v75, 0xffff0000, v124
	v_pk_mul_f32 v[144:145], v[106:107], v[106:107]
	v_pk_mul_f32 v[156:157], v[100:101], v[100:101]
	v_pk_mul_f32 v[166:167], v[90:91], v[90:91]
	v_add_f32_e32 v115, v146, v147
	v_lshlrev_b32_e32 v65, 16, v69
	v_lshlrev_b32_e32 v98, 16, v68
	v_and_b32_e32 v99, 0xffff0000, v68
	v_lshlrev_b32_e32 v68, 16, v125
	v_and_b32_e32 v69, 0xffff0000, v125
	v_pk_mul_f32 v[154:155], v[96:97], v[96:97]
	v_pk_mul_f32 v[164:165], v[86:87], v[86:87]
	v_pk_mul_f32 v[176:177], v[74:75], v[74:75]
	v_add_f32_e32 v146, v156, v157
	v_add_f32_e32 v147, v166, v167
	v_add_f32_e32 v115, v144, v115
	v_lshlrev_b32_e32 v84, 16, v122
	v_and_b32_e32 v85, 0xffff0000, v122
	v_pk_mul_f32 v[142:143], v[104:105], v[104:105]
	v_pk_mul_f32 v[174:175], v[68:69], v[68:69]
	v_add_f32_e32 v156, v176, v177
	v_add_f32_e32 v144, v154, v146
	v_add_f32_e32 v146, v164, v147
	v_add_f32_e32 v115, v145, v115
	v_lshlrev_b32_e32 v81, 16, v62
	v_and_b32_e32 v82, 0xffff0000, v63
	v_lshlrev_b32_e32 v83, 16, v63
	v_lshlrev_b32_e32 v62, 16, v126
	v_and_b32_e32 v63, 0xffff0000, v126
	v_pk_mul_f32 v[152:153], v[94:95], v[94:95]
	v_pk_mul_f32 v[162:163], v[84:85], v[84:85]
	v_add_f32_e32 v147, v174, v156
	v_add_f32_e32 v144, v155, v144
	v_add_f32_e32 v145, v165, v146
	v_add_f32_e32 v115, v142, v115
	v_lshlrev_b32_e32 v76, 16, v123
	v_and_b32_e32 v77, 0xffff0000, v123
	v_pk_mul_f32 v[140:141], v[102:103], v[102:103]
	v_pk_mul_f32 v[172:173], v[62:63], v[62:63]
	v_add_f32_e32 v146, v175, v147
	v_add_f32_e32 v142, v152, v144
	v_add_f32_e32 v144, v162, v145
	v_add_f32_e32 v115, v143, v115
	v_and_b32_e32 v78, 0xffff0000, v61
	v_lshlrev_b32_e32 v79, 16, v61
	v_lshlrev_b32_e32 v108, 16, v60
	v_and_b32_e32 v109, 0xffff0000, v60
	v_lshlrev_b32_e32 v60, 16, v127
	v_and_b32_e32 v61, 0xffff0000, v127
	v_pk_mul_f32 v[150:151], v[92:93], v[92:93]
	v_pk_mul_f32 v[160:161], v[76:77], v[76:77]
	v_add_f32_e32 v145, v172, v146
	v_add_f32_e32 v142, v153, v142
	v_add_f32_e32 v143, v163, v144
	v_add_f32_e32 v115, v140, v115
	v_lshlrev_b32_e32 v88, 16, v72
	v_and_b32_e32 v89, 0xffff0000, v72
	v_pk_mul_f32 v[148:149], v[108:109], v[108:109]
	v_pk_mul_f32 v[170:171], v[60:61], v[60:61]
	v_add_f32_e32 v144, v173, v145
	v_add_f32_e32 v140, v150, v142
	v_add_f32_e32 v142, v160, v143
	v_add_f32_e32 v115, v141, v115
	v_and_b32_e32 v54, 0xffff0000, v73
	v_lshlrev_b32_e32 v55, 16, v73
	v_lshlrev_b32_e32 v72, 16, v116
	v_and_b32_e32 v73, 0xffff0000, v116
	v_pk_mul_f32 v[158:159], v[98:99], v[98:99]
	v_pk_mul_f32 v[168:169], v[88:89], v[88:89]
	v_add_f32_e32 v143, v170, v144
	v_add_f32_e32 v140, v151, v140
	v_add_f32_e32 v141, v161, v142
	v_add_f32_e32 v115, v148, v115
	v_and_b32_e32 v48, 0xffff0000, v117
	v_lshlrev_b32_e32 v49, 16, v117
	v_pk_mul_f32 v[116:117], v[78:79], v[78:79]
	v_pk_mul_f32 v[178:179], v[72:73], v[72:73]
	v_add_f32_e32 v142, v171, v143
	v_add_f32_e32 v140, v158, v140
; __device__ __forceinline__ float wave_sum_fast(float x) { x = reduce16(x); return (rl_(x, 0) + rl_(x, 16)) + (rl_(x, 32) + rl_(x, 48)); }
; __device__ __forceinline__ void norm_mod_bf16_phase(const Ctx& F, const bf16_t* xin, const float* gain, const float* shift, const float* scale) {
;     ...
; #pragma unroll
;             for (int u = 0; u < 4; ++u) { s[u] = 0.f;
; #pragma unroll
;                 for (int j = 0; j < 2; ++j) { float f[8]; unpack8(raw[u][j], f);
; #pragma unroll
;                     for (int e = 0; e < 8; ++e) s[u] += f[e] * f[e]; }
;                 s[u] = wave_sum_fast(s[u]); }
; #pragma unroll
;             for (int u = 0; u < 4; ++u) { const float rstd = 1.0f / sqrtf(s[u] * (1.0f / D) + 1e-6f);
; #pragma unroll
;                 for (int j = 0; j < 2; ++j) { float f[8]; unpack8(raw[u][j], f); float o[8];
; #pragma unroll
;                     for (int e = 0; e < 8; ++e) o[e] = f[e] * rstd * ga[j][e] + sh[j][e];
	v_add_f32_e32 v141, v168, v141
	v_add_f32_e32 v115, v149, v115
	v_pk_mul_f32 v[122:123], v[64:65], v[64:65]
	v_pk_mul_f32 v[128:129], v[54:55], v[54:55]
	v_add_f32_e32 v142, v178, v142
	v_add_f32_e32 v140, v159, v140
	v_add_f32_e32 v141, v169, v141
	v_add_f32_e32 v115, v117, v115
	v_and_b32_e32 v66, 0xffff0000, v70
	v_lshlrev_b32_e32 v67, 16, v70
	v_and_b32_e32 v50, 0xffff0000, v118
	v_lshlrev_b32_e32 v51, 16, v118
	v_and_b32_e32 v52, 0xffff0000, v119
	v_lshlrev_b32_e32 v53, 16, v119
	v_pk_mul_f32 v[118:119], v[80:81], v[80:81]
	v_pk_mul_f32 v[134:135], v[48:49], v[48:49]
	v_add_f32_e32 v142, v179, v142
	v_add_f32_e32 v117, v123, v140
	v_add_f32_e32 v123, v129, v141
	v_add_f32_e32 v115, v116, v115
	v_pk_mul_f32 v[124:125], v[66:67], v[66:67]
	v_pk_mul_f32 v[130:131], v[56:57], v[56:57]
	v_add_f32_e32 v129, v135, v142
	v_add_f32_e32 v116, v122, v117
	v_add_f32_e32 v117, v128, v123
	v_add_f32_e32 v115, v119, v115
	v_and_b32_e32 v70, 0xffff0000, v71
	v_lshlrev_b32_e32 v71, 16, v71
	v_pk_mul_f32 v[120:121], v[82:83], v[82:83]
	v_pk_mul_f32 v[136:137], v[50:51], v[50:51]
	v_add_f32_e32 v122, v134, v129
	v_add_f32_e32 v116, v125, v116
	v_add_f32_e32 v117, v131, v117
	v_add_f32_e32 v115, v118, v115
	v_pk_mul_f32 v[126:127], v[70:71], v[70:71]
	v_pk_mul_f32 v[132:133], v[58:59], v[58:59]
	v_add_f32_e32 v119, v137, v122
	v_add_f32_e32 v116, v124, v116
	v_add_f32_e32 v117, v130, v117
	v_add_f32_e32 v115, v121, v115
	v_pk_mul_f32 v[138:139], v[52:53], v[52:53]
	v_add_f32_e32 v118, v136, v119
	v_add_f32_e32 v116, v127, v116
	v_add_f32_e32 v117, v133, v117
	v_add_f32_e32 v115, v120, v115
	v_add_f32_e32 v118, v139, v118
	v_add_f32_e32 v116, v126, v116
	v_add_f32_e32 v117, v132, v117
	v_add_f32_dpp v115, v115, v115 quad_perm:[1,0,3,2] row_mask:0xf bank_mask:0xf bound_ctrl:1
	v_add_f32_e32 v118, v138, v118
	v_add_f32_dpp v116, v116, v116 quad_perm:[1,0,3,2] row_mask:0xf bank_mask:0xf bound_ctrl:1
	v_add_f32_dpp v117, v117, v117 quad_perm:[1,0,3,2] row_mask:0xf bank_mask:0xf bound_ctrl:1
	v_add_f32_dpp v115, v115, v115 quad_perm:[2,3,0,1] row_mask:0xf bank_mask:0xf bound_ctrl:1
	v_add_f32_dpp v118, v118, v118 quad_perm:[1,0,3,2] row_mask:0xf bank_mask:0xf bound_ctrl:1
	v_add_f32_dpp v116, v116, v116 quad_perm:[2,3,0,1] row_mask:0xf bank_mask:0xf bound_ctrl:1
	v_add_f32_dpp v117, v117, v117 quad_perm:[2,3,0,1] row_mask:0xf bank_mask:0xf bound_ctrl:1
	v_add_f32_dpp v115, v115, v115 row_half_mirror row_mask:0xf bank_mask:0xf bound_ctrl:1
	v_add_f32_dpp v118, v118, v118 quad_perm:[2,3,0,1] row_mask:0xf bank_mask:0xf bound_ctrl:1
	v_add_f32_dpp v116, v116, v116 row_half_mirror row_mask:0xf bank_mask:0xf bound_ctrl:1
	v_add_f32_dpp v117, v117, v117 row_half_mirror row_mask:0xf bank_mask:0xf bound_ctrl:1
	v_add_f32_dpp v115, v115, v115 row_mirror row_mask:0xf bank_mask:0xf bound_ctrl:1
	v_add_f32_dpp v118, v118, v118 row_half_mirror row_mask:0xf bank_mask:0xf bound_ctrl:1
	v_add_f32_dpp v116, v116, v116 row_mirror row_mask:0xf bank_mask:0xf bound_ctrl:1
	v_add_f32_dpp v117, v117, v117 row_mirror row_mask:0xf bank_mask:0xf bound_ctrl:1
	v_readlane_b32 s12, v115, 16
	v_readlane_b32 s13, v115, 48
	v_add_f32_dpp v118, v118, v118 row_mirror row_mask:0xf bank_mask:0xf bound_ctrl:1
	v_readlane_b32 s4, v115, 0
	v_readlane_b32 s5, v115, 32
	v_readlane_b32 s6, v116, 0
	v_readlane_b32 s14, v116, 16
	v_readlane_b32 s7, v116, 32
	v_readlane_b32 s15, v116, 48
	v_readlane_b32 s8, v117, 0
	v_readlane_b32 s16, v117, 16
	v_readlane_b32 s9, v117, 32
	v_readlane_b32 s17, v117, 48
	v_mov_b32_e32 v116, s12
	v_mov_b32_e32 v117, s13
	v_readlane_b32 s10, v118, 0
	v_readlane_b32 s21, v118, 16
	v_readlane_b32 s11, v118, 32
	v_readlane_b32 s23, v118, 48
	v_mov_b32_e32 v118, s14
	v_mov_b32_e32 v119, s15
	v_mov_b32_e32 v120, s16
	v_mov_b32_e32 v121, s17
	v_pk_add_f32 v[116:117], s[4:5], v[116:117]
	v_pk_add_f32 v[118:119], s[6:7], v[118:119]
	v_pk_add_f32 v[120:121], s[8:9], v[120:121]
	v_add_f32_e32 v115, v116, v117
	v_mov_b32_e32 v122, s21
	v_mov_b32_e32 v123, s23
	v_add_f32_e32 v116, v118, v119
	v_add_f32_e32 v117, v120, v121
	v_fmamk_f32 v115, v115, 0x3a800000, v113
	v_pk_add_f32 v[122:123], s[10:11], v[122:123]
	v_fmamk_f32 v116, v116, 0x3a800000, v113
	v_fmamk_f32 v117, v117, 0x3a800000, v113
	v_rsq_f32_e32 v198, v115
	v_add_f32_e32 v118, v122, v123
	v_rsq_f32_e32 v199, v116
	v_rsq_f32_e32 v200, v117
	v_fmamk_f32 v118, v118, 0x3a800000, v113
	v_rsq_f32_e32 v201, v118
	v_mov_b32_e32 v116, v198
	v_pk_mul_f32 v[110:111], v[116:117], v[110:111] op_sel_hi:[0,1]
	v_pk_mul_f32 v[106:107], v[116:117], v[106:107] op_sel_hi:[0,1]
	v_pk_mul_f32 v[104:105], v[116:117], v[104:105] op_sel_hi:[0,1]
	v_pk_mul_f32 v[102:103], v[116:117], v[102:103] op_sel_hi:[0,1]
	v_pk_mul_f32 v[108:109], v[116:117], v[108:109] op_sel_hi:[0,1]
	v_pk_mul_f32 v[78:79], v[116:117], v[78:79] op_sel_hi:[0,1]
	v_pk_mul_f32 v[80:81], v[116:117], v[80:81] op_sel_hi:[0,1]
	v_pk_mul_f32 v[82:83], v[116:117], v[82:83] op_sel_hi:[0,1]
	v_mov_b32_e32 v116, v199
	v_pk_fma_f32 v[110:111], v[24:25], v[110:111], v[0:1]
	v_pk_fma_f32 v[106:107], v[26:27], v[106:107], v[2:3]
	v_pk_fma_f32 v[104:105], v[28:29], v[104:105], v[4:5]
; __device__ __forceinline__ unsigned pk2(float lo, float hi) { f32x2 v = {lo, hi}; bf16x2_t b = __builtin_convertvector(v, bf16x2_t); return __builtin_bit_cast(unsigned, b); }
; __device__ __forceinline__ void norm_mod_bf16_phase(const Ctx& F, const bf16_t* xin, const float* gain, const float* shift, const float* scale) {
;     ...
;             for (int u = 0; u < 4; ++u) { const float rstd = 1.0f / sqrtf(s[u] * (1.0f / D) + 1e-6f);
; #pragma unroll
;                 for (int j = 0; j < 2; ++j) { float f[8]; unpack8(raw[u][j], f); float o[8];
; #pragma unroll
;                     for (int e = 0; e < 8; ++e) o[e] = f[e] * rstd * ga[j][e] + sh[j][e];
;                     u32x4 w; w.x = pk2(o[0], o[1]); w.y = pk2(o[2], o[3]); w.z = pk2(o[4], o[5]); w.w = pk2(o[6], o[7]);
;                     *(u32x4*)(hb + (size_t)(row0 + r + u) * D + 8 * ln + 512 * j) = w; } }
	v_pk_fma_f32 v[102:103], v[30:31], v[102:103], v[6:7]
	v_pk_fma_f32 v[108:109], v[32:33], v[108:109], v[8:9]
	v_pk_fma_f32 v[118:119], v[34:35], v[78:79], v[10:11] op_sel:[0,1,0] op_sel_hi:[1,0,1]
	v_pk_fma_f32 v[80:81], v[36:37], v[80:81], v[12:13] op_sel:[0,1,0] op_sel_hi:[1,0,1]
	v_pk_fma_f32 v[82:83], v[38:39], v[82:83], v[14:15] op_sel:[0,1,0] op_sel_hi:[1,0,1]
	v_pk_mul_f32 v[100:101], v[116:117], v[100:101] op_sel_hi:[0,1]
	v_pk_mul_f32 v[96:97], v[116:117], v[96:97] op_sel_hi:[0,1]
	v_pk_mul_f32 v[94:95], v[116:117], v[94:95] op_sel_hi:[0,1]
	v_pk_mul_f32 v[92:93], v[116:117], v[92:93] op_sel_hi:[0,1]
	v_pk_mul_f32 v[98:99], v[116:117], v[98:99] op_sel_hi:[0,1]
	v_pk_mul_f32 v[120:121], v[116:117], v[64:65] op_sel_hi:[0,1]
	v_pk_mul_f32 v[122:123], v[116:117], v[66:67] op_sel_hi:[0,1]
	v_pk_mul_f32 v[70:71], v[116:117], v[70:71] op_sel_hi:[0,1]
	v_mov_b32_e32 v116, v200
	v_cvt_pk_bf16_f32 v64, v110, v111
	v_cvt_pk_bf16_f32 v65, v106, v107
	v_cvt_pk_bf16_f32 v66, v104, v105
	v_cvt_pk_bf16_f32 v67, v102, v103
	v_cvt_pk_bf16_f32 v78, v108, v109
	v_cvt_pk_bf16_f32 v79, v118, v119
	v_cvt_pk_bf16_f32 v80, v80, v81
	v_cvt_pk_bf16_f32 v81, v82, v83
	v_pk_fma_f32 v[82:83], v[24:25], v[100:101], v[0:1]
	v_pk_fma_f32 v[96:97], v[26:27], v[96:97], v[2:3]
	v_pk_fma_f32 v[94:95], v[28:29], v[94:95], v[4:5]
	v_pk_fma_f32 v[92:93], v[30:31], v[92:93], v[6:7]
	v_pk_fma_f32 v[70:71], v[38:39], v[70:71], v[14:15] op_sel:[0,1,0] op_sel_hi:[1,0,1]
	v_pk_mul_f32 v[90:91], v[116:117], v[90:91] op_sel_hi:[0,1]
	v_pk_mul_f32 v[86:87], v[116:117], v[86:87] op_sel_hi:[0,1]
	v_pk_mul_f32 v[84:85], v[116:117], v[84:85] op_sel_hi:[0,1]
	v_pk_mul_f32 v[76:77], v[116:117], v[76:77] op_sel_hi:[0,1]
	v_pk_mul_f32 v[58:59], v[116:117], v[58:59] op_sel_hi:[0,1]
	v_mov_b32_e32 v108, v201
	v_pk_fma_f32 v[98:99], v[32:33], v[98:99], v[8:9]
	v_pk_fma_f32 v[100:101], v[34:35], v[120:121], v[10:11] op_sel:[0,1,0] op_sel_hi:[1,0,1]
	v_pk_fma_f32 v[102:103], v[36:37], v[122:123], v[12:13] op_sel:[0,1,0] op_sel_hi:[1,0,1]
	v_pk_mul_f32 v[88:89], v[116:117], v[88:89] op_sel_hi:[0,1]
	v_pk_mul_f32 v[104:105], v[116:117], v[54:55] op_sel_hi:[0,1]
	v_pk_mul_f32 v[106:107], v[116:117], v[56:57] op_sel_hi:[0,1]
	global_store_dwordx4 v[46:47], v[64:67], off
	global_store_dwordx4 v[46:47], v[78:81], off offset:1024
	v_cvt_pk_bf16_f32 v54, v82, v83
	v_cvt_pk_bf16_f32 v55, v96, v97
	v_cvt_pk_bf16_f32 v56, v94, v95
	v_cvt_pk_bf16_f32 v57, v92, v93
	v_cvt_pk_bf16_f32 v67, v70, v71
	v_pk_fma_f32 v[46:47], v[24:25], v[90:91], v[0:1]
	v_pk_fma_f32 v[70:71], v[26:27], v[86:87], v[2:3]
	v_pk_fma_f32 v[78:79], v[28:29], v[84:85], v[4:5]
	v_pk_fma_f32 v[76:77], v[30:31], v[76:77], v[6:7]
	v_pk_fma_f32 v[58:59], v[38:39], v[58:59], v[14:15] op_sel:[0,1,0] op_sel_hi:[1,0,1]
	v_pk_mul_f32 v[74:75], v[108:109], v[74:75] op_sel_hi:[0,1]
	v_pk_mul_f32 v[68:69], v[108:109], v[68:69] op_sel_hi:[0,1]
	v_pk_mul_f32 v[62:63], v[108:109], v[62:63] op_sel_hi:[0,1]
	v_pk_mul_f32 v[60:61], v[108:109], v[60:61] op_sel_hi:[0,1]
	v_cvt_pk_bf16_f32 v64, v98, v99
	v_cvt_pk_bf16_f32 v65, v100, v101
	v_cvt_pk_bf16_f32 v66, v102, v103
	v_pk_fma_f32 v[80:81], v[32:33], v[88:89], v[8:9]
	v_pk_fma_f32 v[82:83], v[34:35], v[104:105], v[10:11] op_sel:[0,1,0] op_sel_hi:[1,0,1]
	v_pk_fma_f32 v[84:85], v[36:37], v[106:107], v[12:13] op_sel:[0,1,0] op_sel_hi:[1,0,1]
	v_pk_mul_f32 v[72:73], v[108:109], v[72:73] op_sel_hi:[0,1]
	v_pk_mul_f32 v[86:87], v[108:109], v[48:49] op_sel_hi:[0,1]
	v_pk_mul_f32 v[88:89], v[108:109], v[50:51] op_sel_hi:[0,1]
	v_pk_mul_f32 v[52:53], v[108:109], v[52:53] op_sel_hi:[0,1]
	global_store_dwordx4 v[44:45], v[54:57], off
	global_store_dwordx4 v[44:45], v[64:67], off offset:1024
	v_cvt_pk_bf16_f32 v44, v46, v47
	v_cvt_pk_bf16_f32 v45, v70, v71
	v_cvt_pk_bf16_f32 v46, v78, v79
	v_cvt_pk_bf16_f32 v47, v76, v77
	v_cvt_pk_bf16_f32 v51, v58, v59
	v_pk_fma_f32 v[54:55], v[24:25], v[74:75], v[0:1]
	v_pk_fma_f32 v[56:57], v[26:27], v[68:69], v[2:3]
	v_pk_fma_f32 v[58:59], v[28:29], v[62:63], v[4:5]
	v_pk_fma_f32 v[60:61], v[30:31], v[60:61], v[6:7]
	v_cvt_pk_bf16_f32 v48, v80, v81
	v_cvt_pk_bf16_f32 v49, v82, v83
	v_cvt_pk_bf16_f32 v50, v84, v85
	v_pk_fma_f32 v[62:63], v[32:33], v[72:73], v[8:9]
	v_pk_fma_f32 v[64:65], v[34:35], v[86:87], v[10:11] op_sel:[0,1,0] op_sel_hi:[1,0,1]
	v_pk_fma_f32 v[66:67], v[36:37], v[88:89], v[12:13] op_sel:[0,1,0] op_sel_hi:[1,0,1]
	v_pk_fma_f32 v[52:53], v[38:39], v[52:53], v[14:15] op_sel:[0,1,0] op_sel_hi:[1,0,1]
	global_store_dwordx4 v[42:43], v[44:47], off
	global_store_dwordx4 v[42:43], v[48:51], off offset:1024
	v_cvt_pk_bf16_f32 v42, v54, v55
	v_cvt_pk_bf16_f32 v43, v56, v57
	v_cvt_pk_bf16_f32 v44, v58, v59
	v_cvt_pk_bf16_f32 v45, v60, v61
	v_cvt_pk_bf16_f32 v46, v62, v63
	v_cvt_pk_bf16_f32 v47, v64, v65
	v_cvt_pk_bf16_f32 v48, v66, v67
	v_cvt_pk_bf16_f32 v49, v52, v53
	global_store_dwordx4 v[40:41], v[42:45], off
	global_store_dwordx4 v[40:41], v[46:49], off offset:1024
	s_cbranch_scc0 .LBB0_984
	s_add_i32 s0, s0, s1
	s_add_i32 s18, s18, s3
	s_add_i32 s20, s20, s3
	s_add_i32 s22, s22, s3
	s_add_i32 s24, s24, s3
	s_cmpk_gt_i32 s0, 0x7ff
	s_cbranch_scc0 .LBB0_983

; __device__ __forceinline__ float wave_sum_fast(float x) { x = reduce16(x); return (rl_(x, 0) + rl_(x, 16)) + (rl_(x, 32) + rl_(x, 48)); }
; __device__ __forceinline__ void norm_mod_bf16_phase(const Ctx& F, const bf16_t* xin, const float* gain, const float* shift, const float* scale) {
;     ...
;         for (int r = 0; r < 32; r += 4) {
;             u32x4 raw[4][2]; float s[4];
; #pragma unroll
;             for (int u = 0; u < 4; ++u)
; #pragma unroll
;                 for (int j = 0; j < 2; ++j) raw[u][j] = *(const u32x4*)(xin + (size_t)(row0 + r + u) * D + 8 * ln + 512 * j);
; #pragma unroll
;             for (int u = 0; u < 4; ++u) { s[u] = 0.f;
; #pragma unroll
;                 for (int j = 0; j < 2; ++j) { float f[8]; unpack8(raw[u][j], f);
; #pragma unroll
;                     for (int e = 0; e < 8; ++e) s[u] += f[e] * f[e]; }
;                 s[u] = wave_sum_fast(s[u]); }
.LBB0_1204:
	v_lshl_add_u64 v[42:43], s[28:29], 0, v[24:25]
	v_lshl_add_u64 v[44:45], s[36:37], 0, v[24:25]
	v_lshl_add_u64 v[46:47], s[56:57], 0, v[24:25]
	v_lshl_add_u64 v[48:49], s[34:35], 0, v[24:25]
	global_load_dwordx4 v[62:65], v[42:43], off
	global_load_dwordx4 v[70:73], v[44:45], off
	global_load_dwordx4 v[74:77], v[46:47], off
	global_load_dwordx4 v[118:121], v[48:49], off offset:1024
	global_load_dwordx4 v[86:89], v[42:43], off offset:-1024
	global_load_dwordx4 v[90:93], v[44:45], off offset:-1024
	global_load_dwordx4 v[122:125], v[46:47], off offset:-1024
	global_load_dwordx4 v[126:129], v[48:49], off
	v_lshl_add_u64 v[50:51], s[26:27], 0, v[24:25]
	v_add_co_u32_e32 v48, vcc, s48, v50
	v_lshl_add_u64 v[52:53], s[30:31], 0, v[24:25]
	s_nop 0
	v_addc_co_u32_e32 v49, vcc, 0, v51, vcc
	v_add_co_u32_e32 v46, vcc, s48, v52
	v_lshl_add_u64 v[54:55], s[38:39], 0, v[24:25]
	s_nop 0
	v_addc_co_u32_e32 v47, vcc, 0, v53, vcc
	v_add_co_u32_e32 v44, vcc, s48, v54
	v_lshl_add_u64 v[56:57], s[40:41], 0, v[24:25]
	s_nop 0
	v_addc_co_u32_e32 v45, vcc, 0, v55, vcc
	v_add_co_u32_e32 v42, vcc, s48, v56
	s_add_u32 s26, s26, 0x2000
	s_nop 0
	v_addc_co_u32_e32 v43, vcc, 0, v57, vcc
	s_addc_u32 s27, s27, 0
	s_add_i32 s19, s19, 4
	s_add_u32 s28, s28, 0x2000
	s_addc_u32 s29, s29, 0
	s_add_u32 s30, s30, 0x2000
	s_addc_u32 s31, s31, 0
	s_add_u32 s34, s34, 0x2000
	s_addc_u32 s35, s35, 0
	s_add_u32 s36, s36, 0x2000
	s_addc_u32 s37, s37, 0
	s_add_u32 s38, s38, 0x2000
	s_addc_u32 s39, s39, 0
	s_add_u32 s40, s40, 0x2000
	s_addc_u32 s41, s41, 0
	s_add_u32 s56, s56, 0x2000
	s_addc_u32 s57, s57, 0
	s_cmp_gt_u32 s19, 27
	s_waitcnt vmcnt(7)
	v_and_b32_e32 v82, 0xffff0000, v64
	s_waitcnt vmcnt(6)
	v_and_b32_e32 v66, 0xffff0000, v71
	s_waitcnt vmcnt(5)
	v_and_b32_e32 v58, 0xffff0000, v76
	v_lshlrev_b32_e32 v59, 16, v76
	s_waitcnt vmcnt(3)
	v_lshlrev_b32_e32 v112, 16, v86
	v_and_b32_e32 v113, 0xffff0000, v86
	v_lshlrev_b32_e32 v108, 16, v87
	v_and_b32_e32 v109, 0xffff0000, v87
	s_waitcnt vmcnt(2)
	v_lshlrev_b32_e32 v94, 16, v93
	v_and_b32_e32 v95, 0xffff0000, v93
	v_lshlrev_b32_e32 v96, 16, v92
	v_and_b32_e32 v97, 0xffff0000, v92
	v_lshlrev_b32_e32 v102, 16, v90
	v_and_b32_e32 v103, 0xffff0000, v90
	s_waitcnt vmcnt(1)
	v_lshlrev_b32_e32 v92, 16, v122
	v_and_b32_e32 v93, 0xffff0000, v122
	v_pk_mul_f32 v[148:149], v[112:113], v[112:113]
	v_and_b32_e32 v60, 0xffff0000, v77
	v_lshlrev_b32_e32 v61, 16, v77
	v_lshlrev_b32_e32 v104, 16, v89
	v_and_b32_e32 v105, 0xffff0000, v89
	v_lshlrev_b32_e32 v106, 16, v88
	v_and_b32_e32 v107, 0xffff0000, v88
	v_lshlrev_b32_e32 v98, 16, v91
	v_and_b32_e32 v99, 0xffff0000, v91
	v_lshlrev_b32_e32 v88, 16, v123
	v_and_b32_e32 v89, 0xffff0000, v123
	s_waitcnt vmcnt(0)
	v_lshlrev_b32_e32 v76, 16, v126
	v_and_b32_e32 v77, 0xffff0000, v126
	v_pk_mul_f32 v[146:147], v[108:109], v[108:109]
	v_pk_mul_f32 v[158:159], v[102:103], v[102:103]
	v_pk_mul_f32 v[168:169], v[92:93], v[92:93]
	v_add_f32_e32 v117, v148, v149
	v_lshlrev_b32_e32 v67, 16, v71
	v_lshlrev_b32_e32 v100, 16, v70
	v_and_b32_e32 v101, 0xffff0000, v70
	v_lshlrev_b32_e32 v70, 16, v127
	v_and_b32_e32 v71, 0xffff0000, v127
	v_pk_mul_f32 v[156:157], v[98:99], v[98:99]
	v_pk_mul_f32 v[166:167], v[88:89], v[88:89]
	v_pk_mul_f32 v[178:179], v[76:77], v[76:77]
	v_add_f32_e32 v148, v158, v159
	v_add_f32_e32 v149, v168, v169
	v_add_f32_e32 v117, v146, v117
	v_lshlrev_b32_e32 v86, 16, v124
	v_and_b32_e32 v87, 0xffff0000, v124
	v_pk_mul_f32 v[144:145], v[106:107], v[106:107]
	v_pk_mul_f32 v[176:177], v[70:71], v[70:71]
	v_add_f32_e32 v158, v178, v179
	v_add_f32_e32 v146, v156, v148
	v_add_f32_e32 v148, v166, v149
	v_add_f32_e32 v117, v147, v117
	v_lshlrev_b32_e32 v83, 16, v64
	v_and_b32_e32 v84, 0xffff0000, v65
	v_lshlrev_b32_e32 v85, 16, v65
	v_lshlrev_b32_e32 v64, 16, v128
	v_and_b32_e32 v65, 0xffff0000, v128
	v_pk_mul_f32 v[154:155], v[96:97], v[96:97]
	v_pk_mul_f32 v[164:165], v[86:87], v[86:87]
	v_add_f32_e32 v149, v176, v158
	v_add_f32_e32 v146, v157, v146
	v_add_f32_e32 v147, v167, v148
	v_add_f32_e32 v117, v144, v117
	v_lshlrev_b32_e32 v78, 16, v125
	v_and_b32_e32 v79, 0xffff0000, v125
	v_pk_mul_f32 v[142:143], v[104:105], v[104:105]
	v_pk_mul_f32 v[174:175], v[64:65], v[64:65]
	v_add_f32_e32 v148, v177, v149
	v_add_f32_e32 v144, v154, v146
	v_add_f32_e32 v146, v164, v147
	v_add_f32_e32 v117, v145, v117
	v_and_b32_e32 v80, 0xffff0000, v63
	v_lshlrev_b32_e32 v81, 16, v63
	v_lshlrev_b32_e32 v110, 16, v62
	v_and_b32_e32 v111, 0xffff0000, v62
	v_lshlrev_b32_e32 v62, 16, v129
	v_and_b32_e32 v63, 0xffff0000, v129
	v_pk_mul_f32 v[152:153], v[94:95], v[94:95]
	v_pk_mul_f32 v[162:163], v[78:79], v[78:79]
	v_add_f32_e32 v147, v174, v148
	v_add_f32_e32 v144, v155, v144
	v_add_f32_e32 v145, v165, v146
	v_add_f32_e32 v117, v142, v117
	v_lshlrev_b32_e32 v90, 16, v74
	v_and_b32_e32 v91, 0xffff0000, v74
	v_pk_mul_f32 v[150:151], v[110:111], v[110:111]
	v_pk_mul_f32 v[172:173], v[62:63], v[62:63]
	v_add_f32_e32 v146, v175, v147
	v_add_f32_e32 v142, v152, v144
	v_add_f32_e32 v144, v162, v145
	v_add_f32_e32 v117, v143, v117
	v_and_b32_e32 v56, 0xffff0000, v75
	v_lshlrev_b32_e32 v57, 16, v75
	v_lshlrev_b32_e32 v74, 16, v118
	v_and_b32_e32 v75, 0xffff0000, v118
	v_pk_mul_f32 v[160:161], v[100:101], v[100:101]
	v_pk_mul_f32 v[170:171], v[90:91], v[90:91]
	v_add_f32_e32 v145, v172, v146
	v_add_f32_e32 v142, v153, v142
	v_add_f32_e32 v143, v163, v144
	v_add_f32_e32 v117, v150, v117
	v_and_b32_e32 v50, 0xffff0000, v119
	v_lshlrev_b32_e32 v51, 16, v119
	v_pk_mul_f32 v[118:119], v[80:81], v[80:81]
	v_pk_mul_f32 v[180:181], v[74:75], v[74:75]
	v_add_f32_e32 v144, v173, v145
	v_add_f32_e32 v142, v160, v142
; __device__ __forceinline__ float wave_sum_fast(float x) { x = reduce16(x); return (rl_(x, 0) + rl_(x, 16)) + (rl_(x, 32) + rl_(x, 48)); }
; __device__ __forceinline__ void norm_mod_bf16_phase(const Ctx& F, const bf16_t* xin, const float* gain, const float* shift, const float* scale) {
;     ...
; #pragma unroll
;             for (int u = 0; u < 4; ++u) { s[u] = 0.f;
; #pragma unroll
;                 for (int j = 0; j < 2; ++j) { float f[8]; unpack8(raw[u][j], f);
; #pragma unroll
;                     for (int e = 0; e < 8; ++e) s[u] += f[e] * f[e]; }
;                 s[u] = wave_sum_fast(s[u]); }
; #pragma unroll
;             for (int u = 0; u < 4; ++u) { const float rstd = 1.0f / sqrtf(s[u] * (1.0f / D) + 1e-6f);
; #pragma unroll
;                 for (int j = 0; j < 2; ++j) { float f[8]; unpack8(raw[u][j], f); float o[8];
; #pragma unroll
;                     for (int e = 0; e < 8; ++e) o[e] = f[e] * rstd * ga[j][e] + sh[j][e];
	v_add_f32_e32 v143, v170, v143
	v_add_f32_e32 v117, v151, v117
	v_pk_mul_f32 v[124:125], v[66:67], v[66:67]
	v_pk_mul_f32 v[130:131], v[56:57], v[56:57]
	v_add_f32_e32 v144, v180, v144
	v_add_f32_e32 v142, v161, v142
	v_add_f32_e32 v143, v171, v143
	v_add_f32_e32 v117, v119, v117
	v_and_b32_e32 v68, 0xffff0000, v72
	v_lshlrev_b32_e32 v69, 16, v72
	v_and_b32_e32 v52, 0xffff0000, v120
	v_lshlrev_b32_e32 v53, 16, v120
	v_and_b32_e32 v54, 0xffff0000, v121
	v_lshlrev_b32_e32 v55, 16, v121
	v_pk_mul_f32 v[120:121], v[82:83], v[82:83]
	v_pk_mul_f32 v[136:137], v[50:51], v[50:51]
	v_add_f32_e32 v144, v181, v144
	v_add_f32_e32 v119, v125, v142
	v_add_f32_e32 v125, v131, v143
	v_add_f32_e32 v117, v118, v117
	v_pk_mul_f32 v[126:127], v[68:69], v[68:69]
	v_pk_mul_f32 v[132:133], v[58:59], v[58:59]
	v_add_f32_e32 v131, v137, v144
	v_add_f32_e32 v118, v124, v119
	v_add_f32_e32 v119, v130, v125
	v_add_f32_e32 v117, v121, v117
	v_and_b32_e32 v72, 0xffff0000, v73
	v_lshlrev_b32_e32 v73, 16, v73
	v_pk_mul_f32 v[122:123], v[84:85], v[84:85]
	v_pk_mul_f32 v[138:139], v[52:53], v[52:53]
	v_add_f32_e32 v124, v136, v131
	v_add_f32_e32 v118, v127, v118
	v_add_f32_e32 v119, v133, v119
	v_add_f32_e32 v117, v120, v117
	v_pk_mul_f32 v[128:129], v[72:73], v[72:73]
	v_pk_mul_f32 v[134:135], v[60:61], v[60:61]
	v_add_f32_e32 v121, v139, v124
	v_add_f32_e32 v118, v126, v118
	v_add_f32_e32 v119, v132, v119
	v_add_f32_e32 v117, v123, v117
	v_pk_mul_f32 v[140:141], v[54:55], v[54:55]
	v_add_f32_e32 v120, v138, v121
	v_add_f32_e32 v118, v129, v118
	v_add_f32_e32 v119, v135, v119
	v_add_f32_e32 v117, v122, v117
	v_add_f32_e32 v120, v141, v120
	v_add_f32_e32 v118, v128, v118
	v_add_f32_e32 v119, v134, v119
	v_add_f32_dpp v117, v117, v117 quad_perm:[1,0,3,2] row_mask:0xf bank_mask:0xf bound_ctrl:1
	v_add_f32_e32 v120, v140, v120
	v_add_f32_dpp v118, v118, v118 quad_perm:[1,0,3,2] row_mask:0xf bank_mask:0xf bound_ctrl:1
	v_add_f32_dpp v119, v119, v119 quad_perm:[1,0,3,2] row_mask:0xf bank_mask:0xf bound_ctrl:1
	v_add_f32_dpp v117, v117, v117 quad_perm:[2,3,0,1] row_mask:0xf bank_mask:0xf bound_ctrl:1
	v_add_f32_dpp v120, v120, v120 quad_perm:[1,0,3,2] row_mask:0xf bank_mask:0xf bound_ctrl:1
	v_add_f32_dpp v118, v118, v118 quad_perm:[2,3,0,1] row_mask:0xf bank_mask:0xf bound_ctrl:1
	v_add_f32_dpp v119, v119, v119 quad_perm:[2,3,0,1] row_mask:0xf bank_mask:0xf bound_ctrl:1
	v_add_f32_dpp v117, v117, v117 row_half_mirror row_mask:0xf bank_mask:0xf bound_ctrl:1
	v_add_f32_dpp v120, v120, v120 quad_perm:[2,3,0,1] row_mask:0xf bank_mask:0xf bound_ctrl:1
	v_add_f32_dpp v118, v118, v118 row_half_mirror row_mask:0xf bank_mask:0xf bound_ctrl:1
	v_add_f32_dpp v119, v119, v119 row_half_mirror row_mask:0xf bank_mask:0xf bound_ctrl:1
	v_add_f32_dpp v117, v117, v117 row_mirror row_mask:0xf bank_mask:0xf bound_ctrl:1
	v_add_f32_dpp v120, v120, v120 row_half_mirror row_mask:0xf bank_mask:0xf bound_ctrl:1
	v_add_f32_dpp v118, v118, v118 row_mirror row_mask:0xf bank_mask:0xf bound_ctrl:1
	v_add_f32_dpp v119, v119, v119 row_mirror row_mask:0xf bank_mask:0xf bound_ctrl:1
	v_readlane_b32 s12, v117, 16
	v_readlane_b32 s13, v117, 48
	v_add_f32_dpp v120, v120, v120 row_mirror row_mask:0xf bank_mask:0xf bound_ctrl:1
	v_readlane_b32 s4, v117, 0
	v_readlane_b32 s5, v117, 32
	v_readlane_b32 s6, v118, 0
	v_readlane_b32 s14, v118, 16
	v_readlane_b32 s7, v118, 32
	v_readlane_b32 s15, v118, 48
	v_readlane_b32 s8, v119, 0
	v_readlane_b32 s16, v119, 16
	v_readlane_b32 s9, v119, 32
	v_readlane_b32 s17, v119, 48
	v_mov_b32_e32 v118, s12
	v_mov_b32_e32 v119, s13
	v_readlane_b32 s10, v120, 0
	v_readlane_b32 s21, v120, 16
	v_readlane_b32 s11, v120, 32
	v_readlane_b32 s23, v120, 48
	v_mov_b32_e32 v120, s14
	v_mov_b32_e32 v121, s15
	v_mov_b32_e32 v122, s16
	v_mov_b32_e32 v123, s17
	v_pk_add_f32 v[118:119], s[4:5], v[118:119]
	v_pk_add_f32 v[120:121], s[6:7], v[120:121]
	v_pk_add_f32 v[122:123], s[8:9], v[122:123]
	v_add_f32_e32 v117, v118, v119
	v_mov_b32_e32 v124, s21
	v_mov_b32_e32 v125, s23
	v_add_f32_e32 v118, v120, v121
	v_add_f32_e32 v119, v122, v123
	v_fmamk_f32 v117, v117, 0x3a800000, v115
	v_pk_add_f32 v[124:125], s[10:11], v[124:125]
	v_fmamk_f32 v118, v118, 0x3a800000, v115
	v_fmamk_f32 v119, v119, 0x3a800000, v115
	v_rsq_f32_e32 v200, v117
	v_add_f32_e32 v120, v124, v125
	v_rsq_f32_e32 v201, v118
	v_rsq_f32_e32 v202, v119
	v_fmamk_f32 v120, v120, 0x3a800000, v115
	v_rsq_f32_e32 v203, v120
	v_mov_b32_e32 v118, v200
	v_pk_mul_f32 v[112:113], v[118:119], v[112:113] op_sel_hi:[0,1]
	v_pk_mul_f32 v[108:109], v[118:119], v[108:109] op_sel_hi:[0,1]
	v_pk_mul_f32 v[106:107], v[118:119], v[106:107] op_sel_hi:[0,1]
	v_pk_mul_f32 v[104:105], v[118:119], v[104:105] op_sel_hi:[0,1]
	v_pk_mul_f32 v[110:111], v[118:119], v[110:111] op_sel_hi:[0,1]
	v_pk_mul_f32 v[80:81], v[118:119], v[80:81] op_sel_hi:[0,1]
	v_pk_mul_f32 v[82:83], v[118:119], v[82:83] op_sel_hi:[0,1]
	v_pk_mul_f32 v[84:85], v[118:119], v[84:85] op_sel_hi:[0,1]
	v_mov_b32_e32 v118, v201
	v_pk_fma_f32 v[112:113], v[26:27], v[112:113], v[0:1]
	v_pk_fma_f32 v[108:109], v[28:29], v[108:109], v[2:3]
	v_pk_fma_f32 v[106:107], v[30:31], v[106:107], v[4:5]
; __device__ __forceinline__ unsigned pk2(float lo, float hi) { f32x2 v = {lo, hi}; bf16x2_t b = __builtin_convertvector(v, bf16x2_t); return __builtin_bit_cast(unsigned, b); }
; __device__ __forceinline__ void norm_mod_bf16_phase(const Ctx& F, const bf16_t* xin, const float* gain, const float* shift, const float* scale) {
;     ...
;             for (int u = 0; u < 4; ++u) { const float rstd = 1.0f / sqrtf(s[u] * (1.0f / D) + 1e-6f);
; #pragma unroll
;                 for (int j = 0; j < 2; ++j) { float f[8]; unpack8(raw[u][j], f); float o[8];
; #pragma unroll
;                     for (int e = 0; e < 8; ++e) o[e] = f[e] * rstd * ga[j][e] + sh[j][e];
;                     u32x4 w; w.x = pk2(o[0], o[1]); w.y = pk2(o[2], o[3]); w.z = pk2(o[4], o[5]); w.w = pk2(o[6], o[7]);
;                     *(u32x4*)(hb + (size_t)(row0 + r + u) * D + 8 * ln + 512 * j) = w; } }
	v_pk_fma_f32 v[104:105], v[32:33], v[104:105], v[6:7]
	v_pk_fma_f32 v[110:111], v[34:35], v[110:111], v[8:9]
	v_pk_fma_f32 v[120:121], v[36:37], v[80:81], v[10:11] op_sel:[0,1,0] op_sel_hi:[1,0,1]
	v_pk_fma_f32 v[82:83], v[38:39], v[82:83], v[12:13] op_sel:[0,1,0] op_sel_hi:[1,0,1]
	v_pk_fma_f32 v[84:85], v[40:41], v[84:85], v[14:15] op_sel:[0,1,0] op_sel_hi:[1,0,1]
	v_pk_mul_f32 v[102:103], v[118:119], v[102:103] op_sel_hi:[0,1]
	v_pk_mul_f32 v[98:99], v[118:119], v[98:99] op_sel_hi:[0,1]
	v_pk_mul_f32 v[96:97], v[118:119], v[96:97] op_sel_hi:[0,1]
	v_pk_mul_f32 v[94:95], v[118:119], v[94:95] op_sel_hi:[0,1]
	v_pk_mul_f32 v[100:101], v[118:119], v[100:101] op_sel_hi:[0,1]
	v_pk_mul_f32 v[122:123], v[118:119], v[66:67] op_sel_hi:[0,1]
	v_pk_mul_f32 v[124:125], v[118:119], v[68:69] op_sel_hi:[0,1]
	v_pk_mul_f32 v[72:73], v[118:119], v[72:73] op_sel_hi:[0,1]
	v_mov_b32_e32 v118, v202
	v_cvt_pk_bf16_f32 v66, v112, v113
	v_cvt_pk_bf16_f32 v67, v108, v109
	v_cvt_pk_bf16_f32 v68, v106, v107
	v_cvt_pk_bf16_f32 v69, v104, v105
	v_cvt_pk_bf16_f32 v80, v110, v111
	v_cvt_pk_bf16_f32 v81, v120, v121
	v_cvt_pk_bf16_f32 v82, v82, v83
	v_cvt_pk_bf16_f32 v83, v84, v85
	v_pk_fma_f32 v[84:85], v[26:27], v[102:103], v[0:1]
	v_pk_fma_f32 v[98:99], v[28:29], v[98:99], v[2:3]
	v_pk_fma_f32 v[96:97], v[30:31], v[96:97], v[4:5]
	v_pk_fma_f32 v[94:95], v[32:33], v[94:95], v[6:7]
	v_pk_fma_f32 v[72:73], v[40:41], v[72:73], v[14:15] op_sel:[0,1,0] op_sel_hi:[1,0,1]
	v_pk_mul_f32 v[92:93], v[118:119], v[92:93] op_sel_hi:[0,1]
	v_pk_mul_f32 v[88:89], v[118:119], v[88:89] op_sel_hi:[0,1]
	v_pk_mul_f32 v[86:87], v[118:119], v[86:87] op_sel_hi:[0,1]
	v_pk_mul_f32 v[78:79], v[118:119], v[78:79] op_sel_hi:[0,1]
	v_pk_mul_f32 v[60:61], v[118:119], v[60:61] op_sel_hi:[0,1]
	v_mov_b32_e32 v110, v203
	v_pk_fma_f32 v[100:101], v[34:35], v[100:101], v[8:9]
	v_pk_fma_f32 v[102:103], v[36:37], v[122:123], v[10:11] op_sel:[0,1,0] op_sel_hi:[1,0,1]
	v_pk_fma_f32 v[104:105], v[38:39], v[124:125], v[12:13] op_sel:[0,1,0] op_sel_hi:[1,0,1]
	v_pk_mul_f32 v[90:91], v[118:119], v[90:91] op_sel_hi:[0,1]
	v_pk_mul_f32 v[106:107], v[118:119], v[56:57] op_sel_hi:[0,1]
	v_pk_mul_f32 v[108:109], v[118:119], v[58:59] op_sel_hi:[0,1]
	global_store_dwordx4 v[48:49], v[66:69], off
	global_store_dwordx4 v[48:49], v[80:83], off offset:1024
	v_cvt_pk_bf16_f32 v56, v84, v85
	v_cvt_pk_bf16_f32 v57, v98, v99
	v_cvt_pk_bf16_f32 v58, v96, v97
	v_cvt_pk_bf16_f32 v59, v94, v95
	v_cvt_pk_bf16_f32 v69, v72, v73
	v_pk_fma_f32 v[48:49], v[26:27], v[92:93], v[0:1]
	v_pk_fma_f32 v[72:73], v[28:29], v[88:89], v[2:3]
	v_pk_fma_f32 v[80:81], v[30:31], v[86:87], v[4:5]
	v_pk_fma_f32 v[78:79], v[32:33], v[78:79], v[6:7]
	v_pk_fma_f32 v[60:61], v[40:41], v[60:61], v[14:15] op_sel:[0,1,0] op_sel_hi:[1,0,1]
	v_pk_mul_f32 v[76:77], v[110:111], v[76:77] op_sel_hi:[0,1]
	v_pk_mul_f32 v[70:71], v[110:111], v[70:71] op_sel_hi:[0,1]
	v_pk_mul_f32 v[64:65], v[110:111], v[64:65] op_sel_hi:[0,1]
	v_pk_mul_f32 v[62:63], v[110:111], v[62:63] op_sel_hi:[0,1]
	v_cvt_pk_bf16_f32 v66, v100, v101
	v_cvt_pk_bf16_f32 v67, v102, v103
	v_cvt_pk_bf16_f32 v68, v104, v105
	v_pk_fma_f32 v[82:83], v[34:35], v[90:91], v[8:9]
	v_pk_fma_f32 v[84:85], v[36:37], v[106:107], v[10:11] op_sel:[0,1,0] op_sel_hi:[1,0,1]
	v_pk_fma_f32 v[86:87], v[38:39], v[108:109], v[12:13] op_sel:[0,1,0] op_sel_hi:[1,0,1]
	v_pk_mul_f32 v[74:75], v[110:111], v[74:75] op_sel_hi:[0,1]
	v_pk_mul_f32 v[88:89], v[110:111], v[50:51] op_sel_hi:[0,1]
	v_pk_mul_f32 v[90:91], v[110:111], v[52:53] op_sel_hi:[0,1]
	v_pk_mul_f32 v[54:55], v[110:111], v[54:55] op_sel_hi:[0,1]
	global_store_dwordx4 v[46:47], v[56:59], off
	global_store_dwordx4 v[46:47], v[66:69], off offset:1024
	v_cvt_pk_bf16_f32 v46, v48, v49
	v_cvt_pk_bf16_f32 v47, v72, v73
	v_cvt_pk_bf16_f32 v48, v80, v81
	v_cvt_pk_bf16_f32 v49, v78, v79
	v_cvt_pk_bf16_f32 v53, v60, v61
	v_pk_fma_f32 v[56:57], v[26:27], v[76:77], v[0:1]
	v_pk_fma_f32 v[58:59], v[28:29], v[70:71], v[2:3]
	v_pk_fma_f32 v[60:61], v[30:31], v[64:65], v[4:5]
	v_pk_fma_f32 v[62:63], v[32:33], v[62:63], v[6:7]
	v_cvt_pk_bf16_f32 v50, v82, v83
	v_cvt_pk_bf16_f32 v51, v84, v85
	v_cvt_pk_bf16_f32 v52, v86, v87
	v_pk_fma_f32 v[64:65], v[34:35], v[74:75], v[8:9]
	v_pk_fma_f32 v[66:67], v[36:37], v[88:89], v[10:11] op_sel:[0,1,0] op_sel_hi:[1,0,1]
	v_pk_fma_f32 v[68:69], v[38:39], v[90:91], v[12:13] op_sel:[0,1,0] op_sel_hi:[1,0,1]
	v_pk_fma_f32 v[54:55], v[40:41], v[54:55], v[14:15] op_sel:[0,1,0] op_sel_hi:[1,0,1]
	global_store_dwordx4 v[44:45], v[46:49], off
	global_store_dwordx4 v[44:45], v[50:53], off offset:1024
	v_cvt_pk_bf16_f32 v44, v56, v57
	v_cvt_pk_bf16_f32 v45, v58, v59
	v_cvt_pk_bf16_f32 v46, v60, v61
	v_cvt_pk_bf16_f32 v47, v62, v63
	v_cvt_pk_bf16_f32 v48, v64, v65
	v_cvt_pk_bf16_f32 v49, v66, v67
	v_cvt_pk_bf16_f32 v50, v68, v69
	v_cvt_pk_bf16_f32 v51, v54, v55
	global_store_dwordx4 v[42:43], v[44:47], off
	global_store_dwordx4 v[42:43], v[48:51], off offset:1024
	s_cbranch_scc0 .LBB0_1204
	s_add_i32 s0, s0, s1
	s_add_i32 s18, s18, s3
	s_add_i32 s20, s20, s3
	s_add_i32 s22, s22, s3
	s_add_i32 s24, s24, s3
	s_cmpk_gt_i32 s0, 0x7ff
	s_cbranch_scc0 .LBB0_1203

; __device__ __forceinline__ float wave_sum_fast(float x) { x = reduce16(x); return (rl_(x, 0) + rl_(x, 16)) + (rl_(x, 32) + rl_(x, 48)); }
; __device__ __forceinline__ void final_norm_phase(const Ctx& F) {
;     ...
;     for (int ch = gw; ch < T / 4; ch += NGW) {
;         u32x4 raw[4][2]; float s[4];
; #pragma unroll
;         for (int u = 0; u < 4; ++u)
; #pragma unroll
;             for (int j = 0; j < 2; ++j) raw[u][j] = *(const u32x4*)(xf + (size_t)(4 * ch + u) * D + 8 * ln + 512 * j);
; #pragma unroll
;         for (int u = 0; u < 4; ++u) { s[u] = 0.f;
; #pragma unroll
;             for (int j = 0; j < 2; ++j) { float f[8]; unpack8(raw[u][j], f);
; #pragma unroll
;                 for (int e = 0; e < 8; ++e) s[u] += f[e] * f[e]; }
;             s[u] = wave_sum_fast(s[u]); }
; #pragma unroll
;         for (int u = 0; u < 4; ++u) { const float rstd = 1.0f / sqrtf(s[u] * (1.0f / D) + 1e-6f); float* xr = F.out + (size_t)(4 * ch + u) * D;
; #pragma unroll
;             for (int j = 0; j < 2; ++j) { float f[8]; unpack8(raw[u][j], f);
;                 *(f32x4*)(xr + 8 * ln + 512 * j) = (f32x4){f[0] * rstd * ga[j][0], f[1] * rstd * ga[j][1], f[2] * rstd * ga[j][2], f[3] * rstd * ga[j][3]};
;                 *(f32x4*)(xr + 8 * ln + 512 * j + 4) = (f32x4){f[4] * rstd * ga[j][4], f[5] * rstd * ga[j][5], f[6] * rstd * ga[j][6], f[7] * rstd * ga[j][7]}; } }
.LBB0_1763:
	s_ashr_i32 s3, s2, 31
	s_lshl_b64 s[0:1], s[2:3], 11
	s_add_i32 s8, s2, 1
	v_lshl_add_u64 v[16:17], v[40:41], 0, s[0:1]
	s_ashr_i32 s9, s8, 31
	global_load_dwordx4 v[44:47], v[16:17], off offset:1024
	global_load_dwordx4 v[48:51], v[16:17], off
	s_lshl_b64 s[0:1], s[8:9], 11
	s_add_i32 s6, s2, 2
	v_lshl_add_u64 v[52:53], v[40:41], 0, s[0:1]
	s_ashr_i32 s7, s6, 31
	s_add_i32 s4, s2, 3
	global_load_dwordx4 v[32:35], v[52:53], off offset:1024
	s_lshl_b64 s[0:1], s[6:7], 11
	s_ashr_i32 s5, s4, 31
	v_lshl_add_u64 v[54:55], v[40:41], 0, s[0:1]
	s_lshl_b64 s[0:1], s[4:5], 11
	v_lshl_add_u64 v[56:57], v[40:41], 0, s[0:1]
	global_load_dwordx4 v[24:27], v[54:55], off offset:1024
	global_load_dwordx4 v[16:19], v[56:57], off offset:1024
	global_load_dwordx4 v[36:39], v[52:53], off
	global_load_dwordx4 v[28:31], v[54:55], off
	global_load_dwordx4 v[20:23], v[56:57], off
	s_lshl_b64 s[0:1], s[2:3], 12
	v_lshl_add_u64 v[72:73], v[42:43], 0, s[0:1]
	s_add_i32 s10, s10, s11
	s_add_i32 s2, s2, s12
	s_waitcnt vmcnt(0)
	v_lshlrev_b32_e32 v84, 16, v44
	v_lshlrev_b32_e32 v68, 16, v48
	v_and_b32_e32 v69, 0xffff0000, v48
	v_lshlrev_b32_e32 v70, 16, v49
	v_and_b32_e32 v71, 0xffff0000, v49
	v_pk_mul_f32 v[86:87], v[68:69], v[68:69]
	v_pk_mul_f32 v[88:89], v[70:71], v[70:71]
	v_and_b32_e32 v62, 0xffff0000, v34
	v_lshlrev_b32_e32 v63, 16, v34
	v_and_b32_e32 v56, 0xffff0000, v35
	v_lshlrev_b32_e32 v57, 16, v35
	v_and_b32_e32 v34, 0xffff0000, v17
	v_lshlrev_b32_e32 v35, 16, v17
	v_add_f32_e32 v17, v86, v87
	v_lshlrev_b32_e32 v80, 16, v50
	v_and_b32_e32 v81, 0xffff0000, v50
	v_add_f32_e32 v17, v88, v17
	v_pk_mul_f32 v[90:91], v[80:81], v[80:81]
	v_add_f32_e32 v17, v89, v17
	v_lshlrev_b32_e32 v82, 16, v51
	v_and_b32_e32 v83, 0xffff0000, v51
	v_add_f32_e32 v17, v90, v17
	v_pk_mul_f32 v[92:93], v[82:83], v[82:83]
	v_add_f32_e32 v17, v91, v17
	v_and_b32_e32 v85, 0xffff0000, v44
	v_add_f32_e32 v17, v92, v17
	v_pk_mul_f32 v[94:95], v[84:85], v[84:85]
	v_add_f32_e32 v17, v93, v17
	v_and_b32_e32 v74, 0xffff0000, v45
	v_lshlrev_b32_e32 v75, 16, v45
	v_add_f32_e32 v17, v94, v17
	v_pk_mul_f32 v[50:51], v[74:75], v[74:75]
	v_add_f32_e32 v17, v95, v17
	v_and_b32_e32 v76, 0xffff0000, v46
	v_lshlrev_b32_e32 v77, 16, v46
	v_add_f32_e32 v17, v51, v17
	v_pk_mul_f32 v[52:53], v[76:77], v[76:77]
	v_add_f32_e32 v17, v50, v17
	v_and_b32_e32 v78, 0xffff0000, v47
	v_lshlrev_b32_e32 v79, 16, v47
	v_add_f32_e32 v17, v53, v17
	v_pk_mul_f32 v[54:55], v[78:79], v[78:79]
	v_add_f32_e32 v17, v52, v17
	v_add_f32_e32 v17, v55, v17
	v_add_f32_e32 v17, v54, v17
	v_and_b32_e32 v48, 0xffff0000, v25
	v_lshlrev_b32_e32 v49, 16, v25
	v_add_f32_dpp v17, v17, v17 quad_perm:[1,0,3,2] row_mask:0xf bank_mask:0xf bound_ctrl:1
	v_and_b32_e32 v64, 0xffff0000, v33
	v_lshlrev_b32_e32 v65, 16, v33
	v_add_f32_dpp v17, v17, v17 quad_perm:[2,3,0,1] row_mask:0xf bank_mask:0xf bound_ctrl:1
	v_and_b32_e32 v91, 0xffff0000, v32
	v_pk_mul_f32 v[96:97], v[64:65], v[64:65]
	v_add_f32_dpp v17, v17, v17 row_half_mirror row_mask:0xf bank_mask:0xf bound_ctrl:1
	v_pk_mul_f32 v[98:99], v[62:63], v[62:63]
	v_pk_mul_f32 v[100:101], v[56:57], v[56:57]
	v_add_f32_dpp v17, v17, v17 row_mirror row_mask:0xf bank_mask:0xf bound_ctrl:1
	v_pk_mul_f32 v[60:61], v[48:49], v[48:49]
	v_readlane_b32 s3, v17, 16
	v_readlane_b32 s14, v17, 48
	v_readlane_b32 s0, v17, 0
	v_readlane_b32 s1, v17, 32
	v_mov_b32_e32 v50, s3
	v_mov_b32_e32 v51, s14
	v_pk_add_f32 v[50:51], s[0:1], v[50:51]
	v_and_b32_e32 v46, 0xffff0000, v26
	v_add_f32_e32 v17, v50, v51
	v_fmamk_f32 v17, v17, 0x3a800000, v66
	v_rsq_f32_e32 v120, v17
	v_lshlrev_b32_e32 v47, 16, v26
	v_pk_mul_f32 v[58:59], v[46:47], v[46:47]
	v_and_b32_e32 v44, 0xffff0000, v27
	v_lshlrev_b32_e32 v45, 16, v27
	v_pk_mul_f32 v[86:87], v[44:45], v[44:45]
	v_pk_mul_f32 v[52:53], v[34:35], v[34:35]
	v_and_b32_e32 v26, 0xffff0000, v18
	v_lshlrev_b32_e32 v27, 16, v18
	v_pk_mul_f32 v[50:51], v[26:27], v[26:27]
	v_and_b32_e32 v18, 0xffff0000, v19
	v_lshlrev_b32_e32 v19, 16, v19
	v_pk_mul_f32 v[54:55], v[18:19], v[18:19]
	v_mov_b32_e32 v88, v120
	v_pk_mul_f32 v[68:69], v[88:89], v[68:69] op_sel_hi:[0,1]
	v_pk_mul_f32 v[70:71], v[88:89], v[70:71] op_sel_hi:[0,1]
	s_waitcnt lgkmcnt(0)
	v_pk_mul_f32 v[70:71], v[2:3], v[70:71]
	v_pk_mul_f32 v[68:69], v[0:1], v[68:69]
	global_store_dwordx4 v[72:73], v[68:71], off
	v_lshlrev_b32_e32 v90, 16, v32
	v_pk_mul_f32 v[32:33], v[90:91], v[90:91]
	v_pk_mul_f32 v[68:69], v[88:89], v[80:81] op_sel_hi:[0,1]
	v_pk_mul_f32 v[70:71], v[88:89], v[82:83] op_sel_hi:[0,1]
	v_pk_mul_f32 v[70:71], v[6:7], v[70:71]
	v_pk_mul_f32 v[68:69], v[4:5], v[68:69]
	global_store_dwordx4 v[72:73], v[68:71], off offset:16
	v_lshlrev_b32_e32 v80, 16, v38
	v_and_b32_e32 v81, 0xffff0000, v38
	v_pk_mul_f32 v[68:69], v[88:89], v[84:85] op_sel_hi:[0,1]
	v_pk_mul_f32 v[70:71], v[88:89], v[74:75] op_sel_hi:[0,1]
	v_pk_mul_f32 v[70:71], v[10:11], v[70:71] op_sel:[0,1] op_sel_hi:[1,0]
	v_pk_mul_f32 v[68:69], v[8:9], v[68:69]
	global_store_dwordx4 v[72:73], v[68:71], off offset:2048
	v_pk_mul_f32 v[82:83], v[80:81], v[80:81]
	v_lshlrev_b32_e32 v84, 16, v39
	v_lshlrev_b32_e32 v70, 16, v36
	v_and_b32_e32 v71, 0xffff0000, v36
	v_pk_mul_f32 v[68:69], v[88:89], v[76:77] op_sel_hi:[0,1]
	v_pk_mul_f32 v[74:75], v[70:71], v[70:71]
	v_lshlrev_b32_e32 v76, 16, v37
	v_and_b32_e32 v77, 0xffff0000, v37
	v_pk_mul_f32 v[36:37], v[76:77], v[76:77]
	v_add_f32_e32 v17, v74, v75
	v_add_f32_e32 v17, v36, v17
	v_add_f32_e32 v17, v37, v17
	v_and_b32_e32 v85, 0xffff0000, v39
	v_add_f32_e32 v17, v82, v17
	v_pk_mul_f32 v[38:39], v[84:85], v[84:85]
	v_add_f32_e32 v17, v83, v17
	v_add_f32_e32 v17, v38, v17
	v_add_f32_e32 v17, v39, v17
; __device__ __forceinline__ float wave_sum_fast(float x) { x = reduce16(x); return (rl_(x, 0) + rl_(x, 16)) + (rl_(x, 32) + rl_(x, 48)); }
; __device__ __forceinline__ void final_norm_phase(const Ctx& F) {
;     ...
;         for (int u = 0; u < 4; ++u) { s[u] = 0.f;
; #pragma unroll
;             for (int j = 0; j < 2; ++j) { float f[8]; unpack8(raw[u][j], f);
; #pragma unroll
;                 for (int e = 0; e < 8; ++e) s[u] += f[e] * f[e]; }
;             s[u] = wave_sum_fast(s[u]); }
; #pragma unroll
;         for (int u = 0; u < 4; ++u) { const float rstd = 1.0f / sqrtf(s[u] * (1.0f / D) + 1e-6f); float* xr = F.out + (size_t)(4 * ch + u) * D;
; #pragma unroll
;             for (int j = 0; j < 2; ++j) { float f[8]; unpack8(raw[u][j], f);
;                 *(f32x4*)(xr + 8 * ln + 512 * j) = (f32x4){f[0] * rstd * ga[j][0], f[1] * rstd * ga[j][1], f[2] * rstd * ga[j][2], f[3] * rstd * ga[j][3]};
;                 *(f32x4*)(xr + 8 * ln + 512 * j + 4) = (f32x4){f[4] * rstd * ga[j][4], f[5] * rstd * ga[j][5], f[6] * rstd * ga[j][6], f[7] * rstd * ga[j][7]}; } }
	v_add_f32_e32 v17, v32, v17
	v_add_f32_e32 v17, v33, v17
	v_add_f32_e32 v17, v97, v17
	v_add_f32_e32 v17, v96, v17
	v_add_f32_e32 v17, v99, v17
	v_add_f32_e32 v17, v98, v17
	v_add_f32_e32 v17, v101, v17
	v_add_f32_e32 v17, v100, v17
	v_pk_mul_f32 v[36:37], v[12:13], v[68:69] op_sel:[0,1] op_sel_hi:[1,0]
	v_lshlrev_b32_e32 v74, 16, v31
	v_add_f32_dpp v17, v17, v17 quad_perm:[1,0,3,2] row_mask:0xf bank_mask:0xf bound_ctrl:1
	v_and_b32_e32 v75, 0xffff0000, v31
	s_nop 0
	v_add_f32_dpp v17, v17, v17 quad_perm:[2,3,0,1] row_mask:0xf bank_mask:0xf bound_ctrl:1
	s_nop 1
	v_add_f32_dpp v17, v17, v17 row_half_mirror row_mask:0xf bank_mask:0xf bound_ctrl:1
	s_nop 1
	v_add_f32_dpp v17, v17, v17 row_mirror row_mask:0xf bank_mask:0xf bound_ctrl:1
	s_nop 0
	v_readlane_b32 s3, v17, 16
	v_readlane_b32 s14, v17, 48
	v_readlane_b32 s0, v17, 0
	v_readlane_b32 s1, v17, 32
	v_mov_b32_e32 v32, s3
	v_mov_b32_e32 v33, s14
	v_pk_add_f32 v[32:33], s[0:1], v[32:33]
	s_nop 0
	v_add_f32_e32 v17, v32, v33
	v_fmamk_f32 v17, v17, 0x3a800000, v66
	v_rsq_f32_e32 v121, v17
	v_pk_mul_f32 v[32:33], v[88:89], v[78:79] op_sel_hi:[0,1]
	v_pk_mul_f32 v[38:39], v[14:15], v[32:33] op_sel:[0,1] op_sel_hi:[1,0]
	global_store_dwordx4 v[72:73], v[36:39], off offset:2064
	s_lshl_b64 s[0:1], s[8:9], 12
	v_lshl_add_u64 v[32:33], v[42:43], 0, s[0:1]
	v_mov_b32_e32 v68, v121
	v_pk_mul_f32 v[36:37], v[68:69], v[70:71] op_sel_hi:[0,1]
	v_pk_mul_f32 v[38:39], v[68:69], v[76:77] op_sel_hi:[0,1]
	v_pk_mul_f32 v[38:39], v[2:3], v[38:39]
	v_pk_mul_f32 v[36:37], v[0:1], v[36:37]
	global_store_dwordx4 v[32:33], v[36:39], off
	v_lshlrev_b32_e32 v70, 16, v30
	v_and_b32_e32 v71, 0xffff0000, v30
	v_pk_mul_f32 v[36:37], v[68:69], v[80:81] op_sel_hi:[0,1]
	v_pk_mul_f32 v[38:39], v[68:69], v[84:85] op_sel_hi:[0,1]
	v_pk_mul_f32 v[38:39], v[6:7], v[38:39]
	v_pk_mul_f32 v[36:37], v[4:5], v[36:37]
	global_store_dwordx4 v[32:33], v[36:39], off offset:16
	v_pk_mul_f32 v[72:73], v[70:71], v[70:71]
	v_pk_mul_f32 v[30:31], v[74:75], v[74:75]
	v_pk_mul_f32 v[36:37], v[68:69], v[90:91] op_sel_hi:[0,1]
	v_pk_mul_f32 v[38:39], v[68:69], v[64:65] op_sel_hi:[0,1]
	v_pk_mul_f32 v[38:39], v[10:11], v[38:39] op_sel:[0,1] op_sel_hi:[1,0]
	v_pk_mul_f32 v[36:37], v[8:9], v[36:37]
	global_store_dwordx4 v[32:33], v[36:39], off offset:2048
	v_lshlrev_b32_e32 v64, 16, v29
	v_and_b32_e32 v65, 0xffff0000, v29
	v_lshlrev_b32_e32 v38, 16, v28
	v_and_b32_e32 v39, 0xffff0000, v28
	v_pk_mul_f32 v[36:37], v[68:69], v[62:63] op_sel_hi:[0,1]
	v_pk_mul_f32 v[62:63], v[38:39], v[38:39]
	v_pk_mul_f32 v[28:29], v[64:65], v[64:65]
	v_add_f32_e32 v17, v62, v63
	v_add_f32_e32 v17, v28, v17
	v_add_f32_e32 v17, v29, v17
	v_add_f32_e32 v17, v72, v17
	v_add_f32_e32 v17, v73, v17
	v_lshlrev_b32_e32 v76, 16, v24
	v_and_b32_e32 v77, 0xffff0000, v24
	v_add_f32_e32 v17, v30, v17
	v_pk_mul_f32 v[24:25], v[76:77], v[76:77]
	v_add_f32_e32 v17, v31, v17
	v_add_f32_e32 v17, v24, v17
	v_add_f32_e32 v17, v25, v17
	v_add_f32_e32 v17, v61, v17
	v_add_f32_e32 v17, v60, v17
	v_add_f32_e32 v17, v59, v17
	v_add_f32_e32 v17, v58, v17
	v_add_f32_e32 v17, v87, v17
	v_add_f32_e32 v17, v86, v17
	v_pk_mul_f32 v[28:29], v[12:13], v[36:37] op_sel:[0,1] op_sel_hi:[1,0]
	v_and_b32_e32 v59, 0xffff0000, v16
	v_add_f32_dpp v17, v17, v17 quad_perm:[1,0,3,2] row_mask:0xf bank_mask:0xf bound_ctrl:1
	s_nop 1
	v_add_f32_dpp v17, v17, v17 quad_perm:[2,3,0,1] row_mask:0xf bank_mask:0xf bound_ctrl:1
	s_nop 1
	v_add_f32_dpp v17, v17, v17 row_half_mirror row_mask:0xf bank_mask:0xf bound_ctrl:1
	s_nop 1
	v_add_f32_dpp v17, v17, v17 row_mirror row_mask:0xf bank_mask:0xf bound_ctrl:1
	s_nop 0
	v_readlane_b32 s3, v17, 16
	v_readlane_b32 s8, v17, 48
	v_readlane_b32 s0, v17, 0
	v_readlane_b32 s1, v17, 32
	v_mov_b32_e32 v24, s3
	v_mov_b32_e32 v25, s8
	v_pk_add_f32 v[24:25], s[0:1], v[24:25]
	s_nop 0
	v_add_f32_e32 v17, v24, v25
	v_fmamk_f32 v17, v17, 0x3a800000, v66
	v_rsq_f32_e32 v122, v17
	v_pk_mul_f32 v[24:25], v[68:69], v[56:57] op_sel_hi:[0,1]
	v_pk_mul_f32 v[30:31], v[14:15], v[24:25] op_sel:[0,1] op_sel_hi:[1,0]
	global_store_dwordx4 v[32:33], v[28:31], off offset:2064
	v_lshlrev_b32_e32 v56, 16, v23
; __device__ __forceinline__ float wave_sum_fast(float x) { x = reduce16(x); return (rl_(x, 0) + rl_(x, 16)) + (rl_(x, 32) + rl_(x, 48)); }
; __device__ __forceinline__ void final_norm_phase(const Ctx& F) {
;     ...
;         for (int u = 0; u < 4; ++u) { s[u] = 0.f;
; #pragma unroll
;             for (int j = 0; j < 2; ++j) { float f[8]; unpack8(raw[u][j], f);
; #pragma unroll
;                 for (int e = 0; e < 8; ++e) s[u] += f[e] * f[e]; }
;             s[u] = wave_sum_fast(s[u]); }
; #pragma unroll
;         for (int u = 0; u < 4; ++u) { const float rstd = 1.0f / sqrtf(s[u] * (1.0f / D) + 1e-6f); float* xr = F.out + (size_t)(4 * ch + u) * D;
; #pragma unroll
;             for (int j = 0; j < 2; ++j) { float f[8]; unpack8(raw[u][j], f);
;                 *(f32x4*)(xr + 8 * ln + 512 * j) = (f32x4){f[0] * rstd * ga[j][0], f[1] * rstd * ga[j][1], f[2] * rstd * ga[j][2], f[3] * rstd * ga[j][3]};
;                 *(f32x4*)(xr + 8 * ln + 512 * j + 4) = (f32x4){f[4] * rstd * ga[j][4], f[5] * rstd * ga[j][5], f[6] * rstd * ga[j][6], f[7] * rstd * ga[j][7]}; } }
	v_and_b32_e32 v57, 0xffff0000, v23
	v_lshlrev_b32_e32 v58, 16, v16
	s_nop 0
	s_lshl_b64 s[0:1], s[6:7], 12
	v_lshl_add_u64 v[24:25], v[42:43], 0, s[0:1]
	v_mov_b32_e32 v32, v122
	v_pk_mul_f32 v[28:29], v[32:33], v[38:39] op_sel_hi:[0,1]
	v_pk_mul_f32 v[30:31], v[32:33], v[64:65] op_sel_hi:[0,1]
	v_pk_mul_f32 v[30:31], v[2:3], v[30:31]
	v_pk_mul_f32 v[28:29], v[0:1], v[28:29]
	global_store_dwordx4 v[24:25], v[28:31], off
	v_lshlrev_b32_e32 v38, 16, v21
	v_and_b32_e32 v39, 0xffff0000, v21
	v_pk_mul_f32 v[28:29], v[32:33], v[70:71] op_sel_hi:[0,1]
	v_pk_mul_f32 v[30:31], v[32:33], v[74:75] op_sel_hi:[0,1]
	v_pk_mul_f32 v[30:31], v[6:7], v[30:31]
	v_pk_mul_f32 v[28:29], v[4:5], v[28:29]
	global_store_dwordx4 v[24:25], v[28:31], off offset:16
	v_pk_mul_f32 v[16:17], v[58:59], v[58:59]
	s_nop 0
	v_pk_mul_f32 v[28:29], v[32:33], v[76:77] op_sel_hi:[0,1]
	v_pk_mul_f32 v[30:31], v[32:33], v[48:49] op_sel_hi:[0,1]
	v_pk_mul_f32 v[30:31], v[10:11], v[30:31] op_sel:[0,1] op_sel_hi:[1,0]
	v_pk_mul_f32 v[28:29], v[8:9], v[28:29]
	global_store_dwordx4 v[24:25], v[28:31], off offset:2048
	s_nop 1
	v_lshlrev_b32_e32 v30, 16, v20
	v_and_b32_e32 v31, 0xffff0000, v20
	v_pk_mul_f32 v[36:37], v[30:31], v[30:31]
	v_pk_mul_f32 v[28:29], v[32:33], v[46:47] op_sel_hi:[0,1]
	v_pk_mul_f32 v[20:21], v[38:39], v[38:39]
	v_add_f32_e32 v33, v36, v37
	v_lshlrev_b32_e32 v46, 16, v22
	v_and_b32_e32 v47, 0xffff0000, v22
	v_add_f32_e32 v20, v20, v33
	v_pk_mul_f32 v[48:49], v[46:47], v[46:47]
	v_add_f32_e32 v20, v21, v20
	v_add_f32_e32 v20, v48, v20
	v_pk_mul_f32 v[22:23], v[56:57], v[56:57]
	v_add_f32_e32 v20, v49, v20
	v_add_f32_e32 v20, v22, v20
	v_add_f32_e32 v20, v23, v20
	v_add_f32_e32 v16, v16, v20
	v_add_f32_e32 v16, v17, v16
	v_add_f32_e32 v16, v53, v16
	v_add_f32_e32 v16, v52, v16
	v_add_f32_e32 v16, v51, v16
	v_add_f32_e32 v16, v50, v16
	v_add_f32_e32 v16, v55, v16
	v_add_f32_e32 v16, v54, v16
	v_pk_mul_f32 v[20:21], v[12:13], v[28:29] op_sel:[0,1] op_sel_hi:[1,0]
	s_nop 0
	v_add_f32_dpp v16, v16, v16 quad_perm:[1,0,3,2] row_mask:0xf bank_mask:0xf bound_ctrl:1
	s_nop 1
	v_add_f32_dpp v16, v16, v16 quad_perm:[2,3,0,1] row_mask:0xf bank_mask:0xf bound_ctrl:1
	s_nop 1
	v_add_f32_dpp v16, v16, v16 row_half_mirror row_mask:0xf bank_mask:0xf bound_ctrl:1
	s_nop 1
	v_add_f32_dpp v16, v16, v16 row_mirror row_mask:0xf bank_mask:0xf bound_ctrl:1
	s_nop 0
	v_readlane_b32 s3, v16, 16
	v_readlane_b32 s6, v16, 48
	v_readlane_b32 s0, v16, 0
	v_readlane_b32 s1, v16, 32
	v_mov_b32_e32 v16, s3
	v_mov_b32_e32 v17, s6
	v_pk_add_f32 v[16:17], s[0:1], v[16:17]
	s_nop 0
	v_add_f32_e32 v16, v16, v17
	v_fmamk_f32 v16, v16, 0x3a800000, v66
	v_rsq_f32_e32 v123, v16
	v_pk_mul_f32 v[16:17], v[32:33], v[44:45] op_sel_hi:[0,1]
	v_pk_mul_f32 v[22:23], v[14:15], v[16:17] op_sel:[0,1] op_sel_hi:[1,0]
	global_store_dwordx4 v[24:25], v[20:23], off offset:2064
	s_lshl_b64 s[0:1], s[4:5], 12
	v_lshl_add_u64 v[24:25], v[42:43], 0, s[0:1]
	s_cmpk_lt_i32 s10, 0x4000
	v_mov_b32_e32 v16, v123
	v_pk_mul_f32 v[20:21], v[16:17], v[30:31] op_sel_hi:[0,1]
	v_pk_mul_f32 v[22:23], v[16:17], v[38:39] op_sel_hi:[0,1]
	v_pk_mul_f32 v[22:23], v[2:3], v[22:23]
	v_pk_mul_f32 v[20:21], v[0:1], v[20:21]
	global_store_dwordx4 v[24:25], v[20:23], off
	s_nop 1
	v_pk_mul_f32 v[20:21], v[16:17], v[46:47] op_sel_hi:[0,1]
	v_pk_mul_f32 v[22:23], v[16:17], v[56:57] op_sel_hi:[0,1]
	v_pk_mul_f32 v[22:23], v[6:7], v[22:23]
	v_pk_mul_f32 v[20:21], v[4:5], v[20:21]
	global_store_dwordx4 v[24:25], v[20:23], off offset:16
	s_nop 1
	v_pk_mul_f32 v[20:21], v[16:17], v[58:59] op_sel_hi:[0,1]
	v_pk_mul_f32 v[22:23], v[16:17], v[34:35] op_sel_hi:[0,1]
	v_pk_mul_f32 v[22:23], v[10:11], v[22:23] op_sel:[0,1] op_sel_hi:[1,0]
	v_pk_mul_f32 v[20:21], v[8:9], v[20:21]
	global_store_dwordx4 v[24:25], v[20:23], off offset:2048
	s_nop 1
	v_pk_mul_f32 v[20:21], v[16:17], v[26:27] op_sel_hi:[0,1]
	v_pk_mul_f32 v[16:17], v[16:17], v[18:19] op_sel_hi:[0,1]
	v_pk_mul_f32 v[18:19], v[14:15], v[16:17] op_sel:[0,1] op_sel_hi:[1,0]
	v_pk_mul_f32 v[16:17], v[12:13], v[20:21] op_sel:[0,1] op_sel_hi:[1,0]
	global_store_dwordx4 v[24:25], v[16:19], off offset:2064
	s_cbranch_scc1 .LBB0_1763
